# GEMM K-loops: per 16-MFMA block, loop order n, m, k: the two MFMAs of an accumulator back to back and the B-side fragment kept across four accumulators; bit-identical
# speedup vs baseline: 1.0085x; 1.0040x over previous
.LBB0_90:
	s_add_u32 s29, s76, 0xfff80080
	s_addc_u32 s30, s77, -1
	s_add_i32 s31, 0, 0x10000
	s_cmp_eq_u32 s28, 28
	s_cselect_b32 s85, s22, s30
	s_cselect_b32 s84, s23, s29
	v_add_u32_e32 v158, s31, v160
	s_cselect_b32 s55, s24, s27
	s_cselect_b32 s54, s25, s26
	s_add_i32 s29, 0, 0x14000
	ds_read_b128 v[154:157], v158
	ds_read_b128 v[180:183], v158 offset:1024
	ds_read_b128 v[184:187], v158 offset:2048
	ds_read_b128 v[188:191], v158 offset:3072
	v_add_u32_e32 v158, s29, v160
	ds_read_b128 v[192:195], v158
	ds_read_b128 v[196:199], v158 offset:1024
	ds_read_b128 v[200:203], v158 offset:2048
	ds_read_b128 v[204:207], v158 offset:3072
	v_lshl_add_u64 v[158:159], s[76:77], 0, v[152:153]
	s_add_i32 m0, s13, 0xc000
	ds_read_b128 v[208:211], v162
	ds_read_b128 v[212:215], v162 offset:1024
	ds_read_b128 v[216:219], v162 offset:2048
	ds_read_b128 v[222:225], v162 offset:3072
	ds_read_b128 v[226:229], v162 offset:4096
	ds_read_b128 v[230:233], v162 offset:5120
	ds_read_b128 v[234:237], v162 offset:6144
	ds_read_b128 v[238:241], v162 offset:7168
	global_load_lds_dwordx4 v[158:159], off
	v_lshl_add_u64 v[158:159], s[76:77], 0, v[150:151]
	s_add_i32 m0, s13, 0xe000
	s_nop 0
	global_load_lds_dwordx4 v[158:159], off
	s_waitcnt vmcnt(8)
	s_waitcnt lgkmcnt(0)
	s_barrier
	s_setprio 1
	s_waitcnt lgkmcnt(0)
	v_mfma_f32_16x16x32_bf16 v[128:131], v[154:157], v[208:211], v[128:131]
	v_mfma_f32_16x16x32_bf16 v[128:131], v[180:183], v[212:215], v[128:131]
	v_mfma_f32_16x16x32_bf16 v[120:123], v[154:157], v[216:219], v[120:123]
	v_mfma_f32_16x16x32_bf16 v[120:123], v[180:183], v[222:225], v[120:123]
	v_mfma_f32_16x16x32_bf16 v[104:107], v[154:157], v[226:229], v[104:107]
	v_mfma_f32_16x16x32_bf16 v[104:107], v[180:183], v[230:233], v[104:107]
	v_mfma_f32_16x16x32_bf16 v[88:91], v[154:157], v[234:237], v[88:91]
	v_mfma_f32_16x16x32_bf16 v[88:91], v[180:183], v[238:241], v[88:91]
	v_mfma_f32_16x16x32_bf16 v[124:127], v[184:187], v[208:211], v[124:127]
	v_mfma_f32_16x16x32_bf16 v[124:127], v[188:191], v[212:215], v[124:127]
	v_mfma_f32_16x16x32_bf16 v[112:115], v[184:187], v[216:219], v[112:115]
	v_mfma_f32_16x16x32_bf16 v[112:115], v[188:191], v[222:225], v[112:115]
	v_mfma_f32_16x16x32_bf16 v[96:99], v[184:187], v[226:229], v[96:99]
	v_mfma_f32_16x16x32_bf16 v[96:99], v[188:191], v[230:233], v[96:99]
	v_mfma_f32_16x16x32_bf16 v[80:83], v[184:187], v[234:237], v[80:83]
	v_mfma_f32_16x16x32_bf16 v[80:83], v[188:191], v[238:241], v[80:83]
	s_setprio 0
	s_setprio 1
	v_mfma_f32_16x16x32_bf16 v[116:119], v[192:195], v[208:211], v[116:119]
	v_mfma_f32_16x16x32_bf16 v[116:119], v[196:199], v[212:215], v[116:119]
	v_mfma_f32_16x16x32_bf16 v[100:103], v[192:195], v[216:219], v[100:103]
	v_mfma_f32_16x16x32_bf16 v[100:103], v[196:199], v[222:225], v[100:103]
	v_mfma_f32_16x16x32_bf16 v[84:87], v[192:195], v[226:229], v[84:87]
	v_mfma_f32_16x16x32_bf16 v[84:87], v[196:199], v[230:233], v[84:87]
	v_mfma_f32_16x16x32_bf16 v[72:75], v[192:195], v[234:237], v[72:75]
	v_mfma_f32_16x16x32_bf16 v[72:75], v[196:199], v[238:241], v[72:75]
	v_mfma_f32_16x16x32_bf16 v[108:111], v[200:203], v[208:211], v[108:111]
	v_mfma_f32_16x16x32_bf16 v[108:111], v[204:207], v[212:215], v[108:111]
	v_mfma_f32_16x16x32_bf16 v[92:95], v[200:203], v[216:219], v[92:95]
	v_mfma_f32_16x16x32_bf16 v[92:95], v[204:207], v[222:225], v[92:95]
	v_mfma_f32_16x16x32_bf16 v[76:79], v[200:203], v[226:229], v[76:79]
	v_mfma_f32_16x16x32_bf16 v[76:79], v[204:207], v[230:233], v[76:79]
	v_mfma_f32_16x16x32_bf16 v[68:71], v[200:203], v[234:237], v[68:71]
	v_mfma_f32_16x16x32_bf16 v[68:71], v[204:207], v[238:241], v[68:71]
	s_setprio 0
	s_barrier
	s_add_i32 s30, s31, s12
	v_lshl_add_u64 v[158:159], s[54:55], 0, v[34:35]
	s_mov_b32 m0, s30
	ds_read_b128 v[208:211], v162 offset:16384
	ds_read_b128 v[212:215], v162 offset:17408
	ds_read_b128 v[216:219], v162 offset:18432
	ds_read_b128 v[222:225], v162 offset:19456
	ds_read_b128 v[226:229], v162 offset:20480
	ds_read_b128 v[230:233], v162 offset:21504
	ds_read_b128 v[234:237], v162 offset:22528
	ds_read_b128 v[238:241], v162 offset:23552
	global_load_lds_dwordx4 v[158:159], off
	s_add_i32 m0, s30, 0x2000
	s_add_u32 s30, s54, 0x80000
	v_lshl_add_u64 v[242:243], s[54:55], 0, v[146:147]
	s_addc_u32 s31, s55, 0
	s_add_i32 s29, s29, s12
	global_load_lds_dwordx4 v[242:243], off
	v_lshl_add_u64 v[244:245], s[30:31], 0, v[34:35]
	s_mov_b32 m0, s29
	v_lshl_add_u64 v[246:247], s[84:85], 0, v[144:145]
	global_load_lds_dwordx4 v[244:245], off
	v_lshl_add_u64 v[244:245], s[30:31], 0, v[146:147]
	s_add_i32 m0, s29, 0x2000
	s_nop 0
	global_load_lds_dwordx4 v[244:245], off
	v_lshl_add_u64 v[244:245], s[84:85], 0, v[142:143]
	s_mov_b32 m0, s13
	s_nop 0
	global_load_lds_dwordx4 v[244:245], off
	s_mov_b32 m0, s14
	s_nop 0
	global_load_lds_dwordx4 v[246:247], off
	s_waitcnt vmcnt(8)
	s_waitcnt lgkmcnt(0)
	s_barrier
	s_setprio 1
	s_waitcnt lgkmcnt(0)
	v_mfma_f32_16x16x32_bf16 v[64:67], v[154:157], v[208:211], v[64:67]
	v_mfma_f32_16x16x32_bf16 v[64:67], v[180:183], v[212:215], v[64:67]
	v_mfma_f32_16x16x32_bf16 v[56:59], v[154:157], v[216:219], v[56:59]
	v_mfma_f32_16x16x32_bf16 v[56:59], v[180:183], v[222:225], v[56:59]
	v_mfma_f32_16x16x32_bf16 v[40:43], v[154:157], v[226:229], v[40:43]
	v_mfma_f32_16x16x32_bf16 v[40:43], v[180:183], v[230:233], v[40:43]
	v_mfma_f32_16x16x32_bf16 v[22:25], v[154:157], v[234:237], v[22:25]
	v_mfma_f32_16x16x32_bf16 v[22:25], v[180:183], v[238:241], v[22:25]
	v_mfma_f32_16x16x32_bf16 v[60:63], v[184:187], v[208:211], v[60:63]
	v_mfma_f32_16x16x32_bf16 v[60:63], v[188:191], v[212:215], v[60:63]
	v_mfma_f32_16x16x32_bf16 v[48:51], v[184:187], v[216:219], v[48:51]
	v_mfma_f32_16x16x32_bf16 v[48:51], v[188:191], v[222:225], v[48:51]
	v_mfma_f32_16x16x32_bf16 v[30:33], v[184:187], v[226:229], v[30:33]
	v_mfma_f32_16x16x32_bf16 v[30:33], v[188:191], v[230:233], v[30:33]
	v_mfma_f32_16x16x32_bf16 v[14:17], v[184:187], v[234:237], v[14:17]
	v_mfma_f32_16x16x32_bf16 v[14:17], v[188:191], v[238:241], v[14:17]
	s_setprio 0
	s_setprio 1
	v_mfma_f32_16x16x32_bf16 v[52:55], v[192:195], v[208:211], v[52:55]
	v_mfma_f32_16x16x32_bf16 v[52:55], v[196:199], v[212:215], v[52:55]
	v_mfma_f32_16x16x32_bf16 v[36:39], v[192:195], v[216:219], v[36:39]
	v_mfma_f32_16x16x32_bf16 v[36:39], v[196:199], v[222:225], v[36:39]
	v_mfma_f32_16x16x32_bf16 v[18:21], v[192:195], v[226:229], v[18:21]
	v_mfma_f32_16x16x32_bf16 v[18:21], v[196:199], v[230:233], v[18:21]
	v_mfma_f32_16x16x32_bf16 v[6:9], v[192:195], v[234:237], v[6:9]
	v_mfma_f32_16x16x32_bf16 v[6:9], v[196:199], v[238:241], v[6:9]
	v_mfma_f32_16x16x32_bf16 v[44:47], v[200:203], v[208:211], v[44:47]
	v_mfma_f32_16x16x32_bf16 v[44:47], v[204:207], v[212:215], v[44:47]
	v_mfma_f32_16x16x32_bf16 v[26:29], v[200:203], v[216:219], v[26:29]
	v_mfma_f32_16x16x32_bf16 v[26:29], v[204:207], v[222:225], v[26:29]
	v_mfma_f32_16x16x32_bf16 v[10:13], v[200:203], v[226:229], v[10:13]
	v_mfma_f32_16x16x32_bf16 v[10:13], v[204:207], v[230:233], v[10:13]
	v_mfma_f32_16x16x32_bf16 v[2:5], v[200:203], v[234:237], v[2:5]
	v_mfma_f32_16x16x32_bf16 v[2:5], v[204:207], v[238:241], v[2:5]
	s_setprio 0
	s_barrier
	s_add_i32 s29, 0, 0x18000
	v_add_u32_e32 v163, s29, v160
	s_add_i32 s39, 0, 0x1c000
	ds_read_b128 v[154:157], v163
	ds_read_b128 v[180:183], v163 offset:1024
	ds_read_b128 v[184:187], v163 offset:2048
	ds_read_b128 v[188:191], v163 offset:3072
	v_add_u32_e32 v163, s39, v160
	ds_read_b128 v[192:195], v163
	ds_read_b128 v[196:199], v163 offset:1024
	ds_read_b128 v[200:203], v163 offset:2048
	ds_read_b128 v[204:207], v163 offset:3072
	s_add_u32 s30, s84, 0x80000
	s_addc_u32 s31, s85, 0
	s_mov_b32 m0, s15
	v_lshl_add_u64 v[248:249], s[30:31], 0, v[142:143]
	ds_read_b128 v[208:211], v162 offset:32768
	ds_read_b128 v[212:215], v162 offset:33792
	ds_read_b128 v[216:219], v162 offset:34816
	ds_read_b128 v[222:225], v162 offset:35840
	ds_read_b128 v[226:229], v162 offset:36864
	ds_read_b128 v[230:233], v162 offset:37888
	ds_read_b128 v[234:237], v162 offset:38912
	ds_read_b128 v[238:241], v162 offset:39936
	global_load_lds_dwordx4 v[248:249], off
	v_lshl_add_u64 v[248:249], s[30:31], 0, v[144:145]
	s_mov_b32 m0, s16
	s_nop 0
	global_load_lds_dwordx4 v[248:249], off
	s_waitcnt vmcnt(8)
	s_waitcnt lgkmcnt(0)
	s_barrier
	s_setprio 1
	s_waitcnt lgkmcnt(0)
	v_mfma_f32_16x16x32_bf16 v[128:131], v[154:157], v[208:211], v[128:131]
	v_mfma_f32_16x16x32_bf16 v[128:131], v[180:183], v[212:215], v[128:131]
	v_mfma_f32_16x16x32_bf16 v[120:123], v[154:157], v[216:219], v[120:123]
	v_mfma_f32_16x16x32_bf16 v[120:123], v[180:183], v[222:225], v[120:123]
	v_mfma_f32_16x16x32_bf16 v[104:107], v[154:157], v[226:229], v[104:107]
	v_mfma_f32_16x16x32_bf16 v[104:107], v[180:183], v[230:233], v[104:107]
	v_mfma_f32_16x16x32_bf16 v[88:91], v[154:157], v[234:237], v[88:91]
	v_mfma_f32_16x16x32_bf16 v[88:91], v[180:183], v[238:241], v[88:91]
	v_mfma_f32_16x16x32_bf16 v[124:127], v[184:187], v[208:211], v[124:127]
	v_mfma_f32_16x16x32_bf16 v[124:127], v[188:191], v[212:215], v[124:127]
	v_mfma_f32_16x16x32_bf16 v[112:115], v[184:187], v[216:219], v[112:115]
	v_mfma_f32_16x16x32_bf16 v[112:115], v[188:191], v[222:225], v[112:115]
	v_mfma_f32_16x16x32_bf16 v[96:99], v[184:187], v[226:229], v[96:99]
	v_mfma_f32_16x16x32_bf16 v[96:99], v[188:191], v[230:233], v[96:99]
	v_mfma_f32_16x16x32_bf16 v[80:83], v[184:187], v[234:237], v[80:83]
	v_mfma_f32_16x16x32_bf16 v[80:83], v[188:191], v[238:241], v[80:83]
	s_setprio 0
	s_setprio 1
	v_mfma_f32_16x16x32_bf16 v[116:119], v[192:195], v[208:211], v[116:119]
	v_mfma_f32_16x16x32_bf16 v[116:119], v[196:199], v[212:215], v[116:119]
	v_mfma_f32_16x16x32_bf16 v[100:103], v[192:195], v[216:219], v[100:103]
	v_mfma_f32_16x16x32_bf16 v[100:103], v[196:199], v[222:225], v[100:103]
	v_mfma_f32_16x16x32_bf16 v[84:87], v[192:195], v[226:229], v[84:87]
	v_mfma_f32_16x16x32_bf16 v[84:87], v[196:199], v[230:233], v[84:87]
	v_mfma_f32_16x16x32_bf16 v[72:75], v[192:195], v[234:237], v[72:75]
	v_mfma_f32_16x16x32_bf16 v[72:75], v[196:199], v[238:241], v[72:75]
	v_mfma_f32_16x16x32_bf16 v[108:111], v[200:203], v[208:211], v[108:111]
	v_mfma_f32_16x16x32_bf16 v[108:111], v[204:207], v[212:215], v[108:111]
	v_mfma_f32_16x16x32_bf16 v[92:95], v[200:203], v[216:219], v[92:95]
	v_mfma_f32_16x16x32_bf16 v[92:95], v[204:207], v[222:225], v[92:95]
	v_mfma_f32_16x16x32_bf16 v[76:79], v[200:203], v[226:229], v[76:79]
	v_mfma_f32_16x16x32_bf16 v[76:79], v[204:207], v[230:233], v[76:79]
	v_mfma_f32_16x16x32_bf16 v[68:71], v[200:203], v[234:237], v[68:71]
	v_mfma_f32_16x16x32_bf16 v[68:71], v[204:207], v[238:241], v[68:71]
	s_setprio 0
	s_barrier
	s_add_i32 s29, s29, s12
	v_lshl_add_u64 v[158:159], v[158:159], 0, s[78:79]
	s_mov_b32 m0, s29
	ds_read_b128 v[208:211], v162 offset:49152
	ds_read_b128 v[212:215], v162 offset:50176
	ds_read_b128 v[216:219], v162 offset:51200
	ds_read_b128 v[222:225], v162 offset:52224
	ds_read_b128 v[226:229], v162 offset:53248
	ds_read_b128 v[230:233], v162 offset:54272
	ds_read_b128 v[234:237], v162 offset:55296
	ds_read_b128 v[238:241], v162 offset:56320
	global_load_lds_dwordx4 v[158:159], off
	s_add_i32 m0, s29, 0x2000
	s_add_u32 s30, s54, 0x80080
	v_lshl_add_u64 v[158:159], v[242:243], 0, s[78:79]
	s_addc_u32 s31, s55, 0
	s_add_i32 s29, s39, s12
	global_load_lds_dwordx4 v[158:159], off
	v_lshl_add_u64 v[158:159], s[30:31], 0, v[34:35]
	s_mov_b32 m0, s29
	s_nop 0
	global_load_lds_dwordx4 v[158:159], off
	v_lshl_add_u64 v[158:159], s[30:31], 0, v[146:147]
	s_add_i32 m0, s29, 0x2000
	s_nop 0
	global_load_lds_dwordx4 v[158:159], off
	v_lshl_add_u64 v[158:159], v[244:245], 0, s[78:79]
	s_mov_b32 m0, s18
	s_nop 0
	global_load_lds_dwordx4 v[158:159], off
	v_lshl_add_u64 v[158:159], v[246:247], 0, s[78:79]
	s_mov_b32 m0, s19
	s_nop 0
	global_load_lds_dwordx4 v[158:159], off
	s_waitcnt vmcnt(8)
	s_waitcnt lgkmcnt(0)
	s_barrier
	s_setprio 1
	s_waitcnt lgkmcnt(0)
	v_mfma_f32_16x16x32_bf16 v[64:67], v[154:157], v[208:211], v[64:67]
	v_mfma_f32_16x16x32_bf16 v[64:67], v[180:183], v[212:215], v[64:67]
	v_mfma_f32_16x16x32_bf16 v[56:59], v[154:157], v[216:219], v[56:59]
	v_mfma_f32_16x16x32_bf16 v[56:59], v[180:183], v[222:225], v[56:59]
	v_mfma_f32_16x16x32_bf16 v[40:43], v[154:157], v[226:229], v[40:43]
	v_mfma_f32_16x16x32_bf16 v[40:43], v[180:183], v[230:233], v[40:43]
	v_mfma_f32_16x16x32_bf16 v[22:25], v[154:157], v[234:237], v[22:25]
	v_mfma_f32_16x16x32_bf16 v[22:25], v[180:183], v[238:241], v[22:25]
	v_mfma_f32_16x16x32_bf16 v[60:63], v[184:187], v[208:211], v[60:63]
	v_mfma_f32_16x16x32_bf16 v[60:63], v[188:191], v[212:215], v[60:63]
	v_mfma_f32_16x16x32_bf16 v[48:51], v[184:187], v[216:219], v[48:51]
	v_mfma_f32_16x16x32_bf16 v[48:51], v[188:191], v[222:225], v[48:51]
	v_mfma_f32_16x16x32_bf16 v[30:33], v[184:187], v[226:229], v[30:33]
	v_mfma_f32_16x16x32_bf16 v[30:33], v[188:191], v[230:233], v[30:33]
	v_mfma_f32_16x16x32_bf16 v[14:17], v[184:187], v[234:237], v[14:17]
	v_mfma_f32_16x16x32_bf16 v[14:17], v[188:191], v[238:241], v[14:17]
	s_setprio 0
	s_setprio 1
	v_mfma_f32_16x16x32_bf16 v[52:55], v[192:195], v[208:211], v[52:55]
	v_mfma_f32_16x16x32_bf16 v[52:55], v[196:199], v[212:215], v[52:55]
	v_mfma_f32_16x16x32_bf16 v[36:39], v[192:195], v[216:219], v[36:39]
	v_mfma_f32_16x16x32_bf16 v[36:39], v[196:199], v[222:225], v[36:39]
	v_mfma_f32_16x16x32_bf16 v[18:21], v[192:195], v[226:229], v[18:21]
	v_mfma_f32_16x16x32_bf16 v[18:21], v[196:199], v[230:233], v[18:21]
	v_mfma_f32_16x16x32_bf16 v[6:9], v[192:195], v[234:237], v[6:9]
	v_mfma_f32_16x16x32_bf16 v[6:9], v[196:199], v[238:241], v[6:9]
	v_mfma_f32_16x16x32_bf16 v[44:47], v[200:203], v[208:211], v[44:47]
	v_mfma_f32_16x16x32_bf16 v[44:47], v[204:207], v[212:215], v[44:47]
	v_mfma_f32_16x16x32_bf16 v[26:29], v[200:203], v[216:219], v[26:29]
	v_mfma_f32_16x16x32_bf16 v[26:29], v[204:207], v[222:225], v[26:29]
	v_mfma_f32_16x16x32_bf16 v[10:13], v[200:203], v[226:229], v[10:13]
	v_mfma_f32_16x16x32_bf16 v[10:13], v[204:207], v[230:233], v[10:13]
	v_mfma_f32_16x16x32_bf16 v[2:5], v[200:203], v[234:237], v[2:5]
	v_mfma_f32_16x16x32_bf16 v[2:5], v[204:207], v[238:241], v[2:5]
	s_setprio 0
	s_barrier
	s_add_i32 s28, s28, 2
	s_add_u32 s26, s26, 0x100
	s_addc_u32 s27, s27, 0
	s_add_u32 s76, s76, 0x100
	s_addc_u32 s77, s77, 0
	s_cmp_gt_u32 s28, 29
	s_cbranch_scc0 .LBB0_90
	s_and_b64 vcc, exec, s[52:53]
	s_cbranch_vccz .LBB0_93
	s_barrier

.LBB0_844:
	s_add_u32 s27, s62, 0xffe00080
	s_addc_u32 s28, s63, -1
	s_add_i32 s29, 0, 0x10000
	s_cmp_eq_u32 s26, 28
	s_cselect_b32 s67, s20, s28
	s_cselect_b32 s66, s21, s27
	v_add_u32_e32 v152, s29, v154
	s_cselect_b32 s55, s22, s25
	s_cselect_b32 s54, s23, s24
	s_add_i32 s27, 0, 0x14000
	ds_read_b128 v[158:161], v152
	ds_read_b128 v[180:183], v152 offset:1024
	ds_read_b128 v[184:187], v152 offset:2048
	ds_read_b128 v[188:191], v152 offset:3072
	v_add_u32_e32 v152, s27, v154
	ds_read_b128 v[192:195], v152
	ds_read_b128 v[196:199], v152 offset:1024
	ds_read_b128 v[200:203], v152 offset:2048
	ds_read_b128 v[204:207], v152 offset:3072
	v_lshl_add_u64 v[152:153], s[62:63], 0, v[150:151]
	s_add_i32 m0, s12, 0xc000
	ds_read_b128 v[208:211], v156
	ds_read_b128 v[212:215], v156 offset:1024
	ds_read_b128 v[216:219], v156 offset:2048
	ds_read_b128 v[222:225], v156 offset:3072
	ds_read_b128 v[226:229], v156 offset:4096
	ds_read_b128 v[230:233], v156 offset:5120
	ds_read_b128 v[234:237], v156 offset:6144
	ds_read_b128 v[238:241], v156 offset:7168
	global_load_lds_dwordx4 v[152:153], off
	v_lshl_add_u64 v[152:153], s[62:63], 0, v[148:149]
	s_add_i32 m0, s12, 0xe000
	s_nop 0
	global_load_lds_dwordx4 v[152:153], off
	s_waitcnt vmcnt(8)
	s_waitcnt lgkmcnt(0)
	s_barrier
	s_setprio 1
	s_waitcnt lgkmcnt(0)
	v_mfma_f32_16x16x32_bf16 v[128:131], v[158:161], v[208:211], v[128:131]
	v_mfma_f32_16x16x32_bf16 v[128:131], v[180:183], v[212:215], v[128:131]
	v_mfma_f32_16x16x32_bf16 v[120:123], v[158:161], v[216:219], v[120:123]
	v_mfma_f32_16x16x32_bf16 v[120:123], v[180:183], v[222:225], v[120:123]
	v_mfma_f32_16x16x32_bf16 v[104:107], v[158:161], v[226:229], v[104:107]
	v_mfma_f32_16x16x32_bf16 v[104:107], v[180:183], v[230:233], v[104:107]
	v_mfma_f32_16x16x32_bf16 v[88:91], v[158:161], v[234:237], v[88:91]
	v_mfma_f32_16x16x32_bf16 v[88:91], v[180:183], v[238:241], v[88:91]
	v_mfma_f32_16x16x32_bf16 v[124:127], v[184:187], v[208:211], v[124:127]
	v_mfma_f32_16x16x32_bf16 v[124:127], v[188:191], v[212:215], v[124:127]
	v_mfma_f32_16x16x32_bf16 v[112:115], v[184:187], v[216:219], v[112:115]
	v_mfma_f32_16x16x32_bf16 v[112:115], v[188:191], v[222:225], v[112:115]
	v_mfma_f32_16x16x32_bf16 v[96:99], v[184:187], v[226:229], v[96:99]
	v_mfma_f32_16x16x32_bf16 v[96:99], v[188:191], v[230:233], v[96:99]
	v_mfma_f32_16x16x32_bf16 v[80:83], v[184:187], v[234:237], v[80:83]
	v_mfma_f32_16x16x32_bf16 v[80:83], v[188:191], v[238:241], v[80:83]
	s_setprio 0
	s_setprio 1
	v_mfma_f32_16x16x32_bf16 v[116:119], v[192:195], v[208:211], v[116:119]
	v_mfma_f32_16x16x32_bf16 v[116:119], v[196:199], v[212:215], v[116:119]
	v_mfma_f32_16x16x32_bf16 v[100:103], v[192:195], v[216:219], v[100:103]
	v_mfma_f32_16x16x32_bf16 v[100:103], v[196:199], v[222:225], v[100:103]
	v_mfma_f32_16x16x32_bf16 v[84:87], v[192:195], v[226:229], v[84:87]
	v_mfma_f32_16x16x32_bf16 v[84:87], v[196:199], v[230:233], v[84:87]
	v_mfma_f32_16x16x32_bf16 v[72:75], v[192:195], v[234:237], v[72:75]
	v_mfma_f32_16x16x32_bf16 v[72:75], v[196:199], v[238:241], v[72:75]
	v_mfma_f32_16x16x32_bf16 v[108:111], v[200:203], v[208:211], v[108:111]
	v_mfma_f32_16x16x32_bf16 v[108:111], v[204:207], v[212:215], v[108:111]
	v_mfma_f32_16x16x32_bf16 v[92:95], v[200:203], v[216:219], v[92:95]
	v_mfma_f32_16x16x32_bf16 v[92:95], v[204:207], v[222:225], v[92:95]
	v_mfma_f32_16x16x32_bf16 v[76:79], v[200:203], v[226:229], v[76:79]
	v_mfma_f32_16x16x32_bf16 v[76:79], v[204:207], v[230:233], v[76:79]
	v_mfma_f32_16x16x32_bf16 v[68:71], v[200:203], v[234:237], v[68:71]
	v_mfma_f32_16x16x32_bf16 v[68:71], v[204:207], v[238:241], v[68:71]
	s_setprio 0
	s_barrier
	s_add_i32 s28, s29, s11
	v_lshl_add_u64 v[152:153], s[54:55], 0, v[34:35]
	s_mov_b32 m0, s28
	ds_read_b128 v[208:211], v156 offset:16384
	ds_read_b128 v[212:215], v156 offset:17408
	ds_read_b128 v[216:219], v156 offset:18432
	ds_read_b128 v[222:225], v156 offset:19456
	ds_read_b128 v[226:229], v156 offset:20480
	ds_read_b128 v[230:233], v156 offset:21504
	ds_read_b128 v[234:237], v156 offset:22528
	ds_read_b128 v[238:241], v156 offset:23552
	global_load_lds_dwordx4 v[152:153], off
	s_add_i32 m0, s28, 0x2000
	s_add_u32 s28, s54, 0x80000
	v_lshl_add_u64 v[162:163], s[54:55], 0, v[146:147]
	s_addc_u32 s29, s55, 0
	s_add_i32 s27, s27, s11
	global_load_lds_dwordx4 v[162:163], off
	v_lshl_add_u64 v[242:243], s[28:29], 0, v[34:35]
	s_mov_b32 m0, s27
	v_lshl_add_u64 v[244:245], s[66:67], 0, v[144:145]
	global_load_lds_dwordx4 v[242:243], off
	v_lshl_add_u64 v[242:243], s[28:29], 0, v[146:147]
	s_add_i32 m0, s27, 0x2000
	s_nop 0
	global_load_lds_dwordx4 v[242:243], off
	v_lshl_add_u64 v[242:243], s[66:67], 0, v[142:143]
	s_mov_b32 m0, s12
	s_nop 0
	global_load_lds_dwordx4 v[242:243], off
	s_mov_b32 m0, s13
	s_nop 0
	global_load_lds_dwordx4 v[244:245], off
	s_waitcnt vmcnt(8)
	s_waitcnt lgkmcnt(0)
	s_barrier
	s_setprio 1
	s_waitcnt lgkmcnt(0)
	v_mfma_f32_16x16x32_bf16 v[64:67], v[158:161], v[208:211], v[64:67]
	v_mfma_f32_16x16x32_bf16 v[64:67], v[180:183], v[212:215], v[64:67]
	v_mfma_f32_16x16x32_bf16 v[56:59], v[158:161], v[216:219], v[56:59]
	v_mfma_f32_16x16x32_bf16 v[56:59], v[180:183], v[222:225], v[56:59]
	v_mfma_f32_16x16x32_bf16 v[40:43], v[158:161], v[226:229], v[40:43]
	v_mfma_f32_16x16x32_bf16 v[40:43], v[180:183], v[230:233], v[40:43]
	v_mfma_f32_16x16x32_bf16 v[22:25], v[158:161], v[234:237], v[22:25]
	v_mfma_f32_16x16x32_bf16 v[22:25], v[180:183], v[238:241], v[22:25]
	v_mfma_f32_16x16x32_bf16 v[60:63], v[184:187], v[208:211], v[60:63]
	v_mfma_f32_16x16x32_bf16 v[60:63], v[188:191], v[212:215], v[60:63]
	v_mfma_f32_16x16x32_bf16 v[48:51], v[184:187], v[216:219], v[48:51]
	v_mfma_f32_16x16x32_bf16 v[48:51], v[188:191], v[222:225], v[48:51]
	v_mfma_f32_16x16x32_bf16 v[30:33], v[184:187], v[226:229], v[30:33]
	v_mfma_f32_16x16x32_bf16 v[30:33], v[188:191], v[230:233], v[30:33]
	v_mfma_f32_16x16x32_bf16 v[14:17], v[184:187], v[234:237], v[14:17]
	v_mfma_f32_16x16x32_bf16 v[14:17], v[188:191], v[238:241], v[14:17]
	s_setprio 0
	s_setprio 1
	v_mfma_f32_16x16x32_bf16 v[52:55], v[192:195], v[208:211], v[52:55]
	v_mfma_f32_16x16x32_bf16 v[52:55], v[196:199], v[212:215], v[52:55]
	v_mfma_f32_16x16x32_bf16 v[36:39], v[192:195], v[216:219], v[36:39]
	v_mfma_f32_16x16x32_bf16 v[36:39], v[196:199], v[222:225], v[36:39]
	v_mfma_f32_16x16x32_bf16 v[18:21], v[192:195], v[226:229], v[18:21]
	v_mfma_f32_16x16x32_bf16 v[18:21], v[196:199], v[230:233], v[18:21]
	v_mfma_f32_16x16x32_bf16 v[6:9], v[192:195], v[234:237], v[6:9]
	v_mfma_f32_16x16x32_bf16 v[6:9], v[196:199], v[238:241], v[6:9]
	v_mfma_f32_16x16x32_bf16 v[44:47], v[200:203], v[208:211], v[44:47]
	v_mfma_f32_16x16x32_bf16 v[44:47], v[204:207], v[212:215], v[44:47]
	v_mfma_f32_16x16x32_bf16 v[26:29], v[200:203], v[216:219], v[26:29]
	v_mfma_f32_16x16x32_bf16 v[26:29], v[204:207], v[222:225], v[26:29]
	v_mfma_f32_16x16x32_bf16 v[10:13], v[200:203], v[226:229], v[10:13]
	v_mfma_f32_16x16x32_bf16 v[10:13], v[204:207], v[230:233], v[10:13]
	v_mfma_f32_16x16x32_bf16 v[2:5], v[200:203], v[234:237], v[2:5]
	v_mfma_f32_16x16x32_bf16 v[2:5], v[204:207], v[238:241], v[2:5]
	s_setprio 0
	s_barrier
	s_add_i32 s27, 0, 0x18000
	v_add_u32_e32 v157, s27, v154
	s_add_i32 s30, 0, 0x1c000
	ds_read_b128 v[158:161], v157
	ds_read_b128 v[180:183], v157 offset:1024
	ds_read_b128 v[184:187], v157 offset:2048
	ds_read_b128 v[188:191], v157 offset:3072
	v_add_u32_e32 v157, s30, v154
	ds_read_b128 v[192:195], v157
	ds_read_b128 v[196:199], v157 offset:1024
	ds_read_b128 v[200:203], v157 offset:2048
	ds_read_b128 v[204:207], v157 offset:3072
	s_add_u32 s28, s66, 0x200000
	s_addc_u32 s29, s67, 0
	s_mov_b32 m0, s14
	v_lshl_add_u64 v[246:247], s[28:29], 0, v[142:143]
	ds_read_b128 v[208:211], v156 offset:32768
	ds_read_b128 v[212:215], v156 offset:33792
	ds_read_b128 v[216:219], v156 offset:34816
	ds_read_b128 v[222:225], v156 offset:35840
	ds_read_b128 v[226:229], v156 offset:36864
	ds_read_b128 v[230:233], v156 offset:37888
	ds_read_b128 v[234:237], v156 offset:38912
	ds_read_b128 v[238:241], v156 offset:39936
	global_load_lds_dwordx4 v[246:247], off
	v_lshl_add_u64 v[246:247], s[28:29], 0, v[144:145]
	s_mov_b32 m0, s15
	s_nop 0
	global_load_lds_dwordx4 v[246:247], off
	s_waitcnt vmcnt(8)
	s_waitcnt lgkmcnt(0)
	s_barrier
	s_setprio 1
	s_waitcnt lgkmcnt(0)
	v_mfma_f32_16x16x32_bf16 v[128:131], v[158:161], v[208:211], v[128:131]
	v_mfma_f32_16x16x32_bf16 v[128:131], v[180:183], v[212:215], v[128:131]
	v_mfma_f32_16x16x32_bf16 v[120:123], v[158:161], v[216:219], v[120:123]
	v_mfma_f32_16x16x32_bf16 v[120:123], v[180:183], v[222:225], v[120:123]
	v_mfma_f32_16x16x32_bf16 v[104:107], v[158:161], v[226:229], v[104:107]
	v_mfma_f32_16x16x32_bf16 v[104:107], v[180:183], v[230:233], v[104:107]
	v_mfma_f32_16x16x32_bf16 v[88:91], v[158:161], v[234:237], v[88:91]
	v_mfma_f32_16x16x32_bf16 v[88:91], v[180:183], v[238:241], v[88:91]
	v_mfma_f32_16x16x32_bf16 v[124:127], v[184:187], v[208:211], v[124:127]
	v_mfma_f32_16x16x32_bf16 v[124:127], v[188:191], v[212:215], v[124:127]
	v_mfma_f32_16x16x32_bf16 v[112:115], v[184:187], v[216:219], v[112:115]
	v_mfma_f32_16x16x32_bf16 v[112:115], v[188:191], v[222:225], v[112:115]
	v_mfma_f32_16x16x32_bf16 v[96:99], v[184:187], v[226:229], v[96:99]
	v_mfma_f32_16x16x32_bf16 v[96:99], v[188:191], v[230:233], v[96:99]
	v_mfma_f32_16x16x32_bf16 v[80:83], v[184:187], v[234:237], v[80:83]
	v_mfma_f32_16x16x32_bf16 v[80:83], v[188:191], v[238:241], v[80:83]
	s_setprio 0
	s_setprio 1
	v_mfma_f32_16x16x32_bf16 v[116:119], v[192:195], v[208:211], v[116:119]
	v_mfma_f32_16x16x32_bf16 v[116:119], v[196:199], v[212:215], v[116:119]
	v_mfma_f32_16x16x32_bf16 v[100:103], v[192:195], v[216:219], v[100:103]
	v_mfma_f32_16x16x32_bf16 v[100:103], v[196:199], v[222:225], v[100:103]
	v_mfma_f32_16x16x32_bf16 v[84:87], v[192:195], v[226:229], v[84:87]
	v_mfma_f32_16x16x32_bf16 v[84:87], v[196:199], v[230:233], v[84:87]
	v_mfma_f32_16x16x32_bf16 v[72:75], v[192:195], v[234:237], v[72:75]
	v_mfma_f32_16x16x32_bf16 v[72:75], v[196:199], v[238:241], v[72:75]
	v_mfma_f32_16x16x32_bf16 v[108:111], v[200:203], v[208:211], v[108:111]
	v_mfma_f32_16x16x32_bf16 v[108:111], v[204:207], v[212:215], v[108:111]
	v_mfma_f32_16x16x32_bf16 v[92:95], v[200:203], v[216:219], v[92:95]
	v_mfma_f32_16x16x32_bf16 v[92:95], v[204:207], v[222:225], v[92:95]
	v_mfma_f32_16x16x32_bf16 v[76:79], v[200:203], v[226:229], v[76:79]
	v_mfma_f32_16x16x32_bf16 v[76:79], v[204:207], v[230:233], v[76:79]
	v_mfma_f32_16x16x32_bf16 v[68:71], v[200:203], v[234:237], v[68:71]
	v_mfma_f32_16x16x32_bf16 v[68:71], v[204:207], v[238:241], v[68:71]
	s_setprio 0
	s_barrier
	s_add_i32 s27, s27, s11
	v_lshl_add_u64 v[152:153], v[152:153], 0, s[78:79]
	s_mov_b32 m0, s27
	ds_read_b128 v[208:211], v156 offset:49152
	ds_read_b128 v[212:215], v156 offset:50176
	ds_read_b128 v[216:219], v156 offset:51200
	ds_read_b128 v[222:225], v156 offset:52224
	ds_read_b128 v[226:229], v156 offset:53248
	ds_read_b128 v[230:233], v156 offset:54272
	ds_read_b128 v[234:237], v156 offset:55296
	ds_read_b128 v[238:241], v156 offset:56320
	global_load_lds_dwordx4 v[152:153], off
	s_add_i32 m0, s27, 0x2000
	s_add_u32 s28, s54, 0x80080
	v_lshl_add_u64 v[152:153], v[162:163], 0, s[78:79]
	s_addc_u32 s29, s55, 0
	s_add_i32 s27, s30, s11
	global_load_lds_dwordx4 v[152:153], off
	v_lshl_add_u64 v[152:153], s[28:29], 0, v[34:35]
	s_mov_b32 m0, s27
	s_nop 0
	global_load_lds_dwordx4 v[152:153], off
	v_lshl_add_u64 v[152:153], s[28:29], 0, v[146:147]
	s_add_i32 m0, s27, 0x2000
	s_nop 0
	global_load_lds_dwordx4 v[152:153], off
	v_lshl_add_u64 v[152:153], v[242:243], 0, s[78:79]
	s_mov_b32 m0, s16
	s_nop 0
	global_load_lds_dwordx4 v[152:153], off
	v_lshl_add_u64 v[152:153], v[244:245], 0, s[78:79]
	s_mov_b32 m0, s17
	s_nop 0
	global_load_lds_dwordx4 v[152:153], off
	s_waitcnt vmcnt(8)
	s_waitcnt lgkmcnt(0)
	s_barrier
	s_setprio 1
	s_waitcnt lgkmcnt(0)
	v_mfma_f32_16x16x32_bf16 v[64:67], v[158:161], v[208:211], v[64:67]
	v_mfma_f32_16x16x32_bf16 v[64:67], v[180:183], v[212:215], v[64:67]
	v_mfma_f32_16x16x32_bf16 v[56:59], v[158:161], v[216:219], v[56:59]
	v_mfma_f32_16x16x32_bf16 v[56:59], v[180:183], v[222:225], v[56:59]
	v_mfma_f32_16x16x32_bf16 v[40:43], v[158:161], v[226:229], v[40:43]
	v_mfma_f32_16x16x32_bf16 v[40:43], v[180:183], v[230:233], v[40:43]
	v_mfma_f32_16x16x32_bf16 v[22:25], v[158:161], v[234:237], v[22:25]
	v_mfma_f32_16x16x32_bf16 v[22:25], v[180:183], v[238:241], v[22:25]
	v_mfma_f32_16x16x32_bf16 v[60:63], v[184:187], v[208:211], v[60:63]
	v_mfma_f32_16x16x32_bf16 v[60:63], v[188:191], v[212:215], v[60:63]
	v_mfma_f32_16x16x32_bf16 v[48:51], v[184:187], v[216:219], v[48:51]
	v_mfma_f32_16x16x32_bf16 v[48:51], v[188:191], v[222:225], v[48:51]
	v_mfma_f32_16x16x32_bf16 v[30:33], v[184:187], v[226:229], v[30:33]
	v_mfma_f32_16x16x32_bf16 v[30:33], v[188:191], v[230:233], v[30:33]
	v_mfma_f32_16x16x32_bf16 v[14:17], v[184:187], v[234:237], v[14:17]
	v_mfma_f32_16x16x32_bf16 v[14:17], v[188:191], v[238:241], v[14:17]
	s_setprio 0
	s_setprio 1
	v_mfma_f32_16x16x32_bf16 v[52:55], v[192:195], v[208:211], v[52:55]
	v_mfma_f32_16x16x32_bf16 v[52:55], v[196:199], v[212:215], v[52:55]
	v_mfma_f32_16x16x32_bf16 v[36:39], v[192:195], v[216:219], v[36:39]
	v_mfma_f32_16x16x32_bf16 v[36:39], v[196:199], v[222:225], v[36:39]
	v_mfma_f32_16x16x32_bf16 v[18:21], v[192:195], v[226:229], v[18:21]
	v_mfma_f32_16x16x32_bf16 v[18:21], v[196:199], v[230:233], v[18:21]
	v_mfma_f32_16x16x32_bf16 v[6:9], v[192:195], v[234:237], v[6:9]
	v_mfma_f32_16x16x32_bf16 v[6:9], v[196:199], v[238:241], v[6:9]
	v_mfma_f32_16x16x32_bf16 v[44:47], v[200:203], v[208:211], v[44:47]
	v_mfma_f32_16x16x32_bf16 v[44:47], v[204:207], v[212:215], v[44:47]
	v_mfma_f32_16x16x32_bf16 v[26:29], v[200:203], v[216:219], v[26:29]
	v_mfma_f32_16x16x32_bf16 v[26:29], v[204:207], v[222:225], v[26:29]
	v_mfma_f32_16x16x32_bf16 v[10:13], v[200:203], v[226:229], v[10:13]
	v_mfma_f32_16x16x32_bf16 v[10:13], v[204:207], v[230:233], v[10:13]
	v_mfma_f32_16x16x32_bf16 v[2:5], v[200:203], v[234:237], v[2:5]
	v_mfma_f32_16x16x32_bf16 v[2:5], v[204:207], v[238:241], v[2:5]
	s_setprio 0
	s_barrier
	s_add_i32 s26, s26, 2
	s_add_u32 s24, s24, 0x100
	s_addc_u32 s25, s25, 0
	s_add_u32 s62, s62, 0x100
	s_addc_u32 s63, s63, 0
	s_cmp_gt_u32 s26, 29
	s_cbranch_scc0 .LBB0_844
	s_and_b64 vcc, exec, s[44:45]
	s_cbranch_vccz .LBB0_847
	s_barrier

.LBB0_985:
	s_add_u32 s27, s62, 0xfff80080
	s_addc_u32 s28, s63, -1
	s_add_i32 s29, 0, 0x10000
	s_cmp_eq_u32 s26, 28
	s_cselect_b32 s67, s20, s28
	s_cselect_b32 s66, s21, s27
	v_add_u32_e32 v152, s29, v154
	s_cselect_b32 s55, s22, s25
	s_cselect_b32 s54, s23, s24
	s_add_i32 s27, 0, 0x14000
	ds_read_b128 v[158:161], v152
	ds_read_b128 v[180:183], v152 offset:1024
	ds_read_b128 v[184:187], v152 offset:2048
	ds_read_b128 v[188:191], v152 offset:3072
	v_add_u32_e32 v152, s27, v154
	ds_read_b128 v[192:195], v152
	ds_read_b128 v[196:199], v152 offset:1024
	ds_read_b128 v[200:203], v152 offset:2048
	ds_read_b128 v[204:207], v152 offset:3072
	v_lshl_add_u64 v[152:153], s[62:63], 0, v[150:151]
	s_add_i32 m0, s12, 0xc000
	ds_read_b128 v[208:211], v156
	ds_read_b128 v[212:215], v156 offset:1024
	ds_read_b128 v[216:219], v156 offset:2048
	ds_read_b128 v[222:225], v156 offset:3072
	ds_read_b128 v[226:229], v156 offset:4096
	ds_read_b128 v[230:233], v156 offset:5120
	ds_read_b128 v[234:237], v156 offset:6144
	ds_read_b128 v[238:241], v156 offset:7168
	global_load_lds_dwordx4 v[152:153], off
	v_lshl_add_u64 v[152:153], s[62:63], 0, v[148:149]
	s_add_i32 m0, s12, 0xe000
	s_nop 0
	global_load_lds_dwordx4 v[152:153], off
	s_waitcnt vmcnt(8)
	s_waitcnt lgkmcnt(0)
	s_barrier
	s_setprio 1
	s_waitcnt lgkmcnt(0)
	v_mfma_f32_16x16x32_bf16 v[128:131], v[158:161], v[208:211], v[128:131]
	v_mfma_f32_16x16x32_bf16 v[128:131], v[180:183], v[212:215], v[128:131]
	v_mfma_f32_16x16x32_bf16 v[112:115], v[158:161], v[216:219], v[112:115]
	v_mfma_f32_16x16x32_bf16 v[112:115], v[180:183], v[222:225], v[112:115]
	v_mfma_f32_16x16x32_bf16 v[96:99], v[158:161], v[226:229], v[96:99]
	v_mfma_f32_16x16x32_bf16 v[96:99], v[180:183], v[230:233], v[96:99]
	v_mfma_f32_16x16x32_bf16 v[80:83], v[158:161], v[234:237], v[80:83]
	v_mfma_f32_16x16x32_bf16 v[80:83], v[180:183], v[238:241], v[80:83]
	v_mfma_f32_16x16x32_bf16 v[124:127], v[184:187], v[208:211], v[124:127]
	v_mfma_f32_16x16x32_bf16 v[124:127], v[188:191], v[212:215], v[124:127]
	v_mfma_f32_16x16x32_bf16 v[108:111], v[184:187], v[216:219], v[108:111]
	v_mfma_f32_16x16x32_bf16 v[108:111], v[188:191], v[222:225], v[108:111]
	v_mfma_f32_16x16x32_bf16 v[92:95], v[184:187], v[226:229], v[92:95]
	v_mfma_f32_16x16x32_bf16 v[92:95], v[188:191], v[230:233], v[92:95]
	v_mfma_f32_16x16x32_bf16 v[76:79], v[184:187], v[234:237], v[76:79]
	v_mfma_f32_16x16x32_bf16 v[76:79], v[188:191], v[238:241], v[76:79]
	s_setprio 0
	s_setprio 1
	v_mfma_f32_16x16x32_bf16 v[120:123], v[192:195], v[208:211], v[120:123]
	v_mfma_f32_16x16x32_bf16 v[120:123], v[196:199], v[212:215], v[120:123]
	v_mfma_f32_16x16x32_bf16 v[104:107], v[192:195], v[216:219], v[104:107]
	v_mfma_f32_16x16x32_bf16 v[104:107], v[196:199], v[222:225], v[104:107]
	v_mfma_f32_16x16x32_bf16 v[88:91], v[192:195], v[226:229], v[88:91]
	v_mfma_f32_16x16x32_bf16 v[88:91], v[196:199], v[230:233], v[88:91]
	v_mfma_f32_16x16x32_bf16 v[72:75], v[192:195], v[234:237], v[72:75]
	v_mfma_f32_16x16x32_bf16 v[72:75], v[196:199], v[238:241], v[72:75]
	v_mfma_f32_16x16x32_bf16 v[116:119], v[200:203], v[208:211], v[116:119]
	v_mfma_f32_16x16x32_bf16 v[116:119], v[204:207], v[212:215], v[116:119]
	v_mfma_f32_16x16x32_bf16 v[100:103], v[200:203], v[216:219], v[100:103]
	v_mfma_f32_16x16x32_bf16 v[100:103], v[204:207], v[222:225], v[100:103]
	v_mfma_f32_16x16x32_bf16 v[84:87], v[200:203], v[226:229], v[84:87]
	v_mfma_f32_16x16x32_bf16 v[84:87], v[204:207], v[230:233], v[84:87]
	v_mfma_f32_16x16x32_bf16 v[68:71], v[200:203], v[234:237], v[68:71]
	v_mfma_f32_16x16x32_bf16 v[68:71], v[204:207], v[238:241], v[68:71]
	s_setprio 0
	s_barrier
	s_add_i32 s28, s29, s11
	v_lshl_add_u64 v[152:153], s[54:55], 0, v[34:35]
	s_mov_b32 m0, s28
	ds_read_b128 v[208:211], v156 offset:16384
	ds_read_b128 v[212:215], v156 offset:17408
	ds_read_b128 v[216:219], v156 offset:18432
	ds_read_b128 v[222:225], v156 offset:19456
	ds_read_b128 v[226:229], v156 offset:20480
	ds_read_b128 v[230:233], v156 offset:21504
	ds_read_b128 v[234:237], v156 offset:22528
	ds_read_b128 v[238:241], v156 offset:23552
	global_load_lds_dwordx4 v[152:153], off
	s_add_i32 m0, s28, 0x2000
	s_add_u32 s28, s54, 0x80000
	v_lshl_add_u64 v[162:163], s[54:55], 0, v[146:147]
	s_addc_u32 s29, s55, 0
	s_add_i32 s27, s27, s11
	global_load_lds_dwordx4 v[162:163], off
	v_lshl_add_u64 v[242:243], s[28:29], 0, v[34:35]
	s_mov_b32 m0, s27
	v_lshl_add_u64 v[244:245], s[66:67], 0, v[144:145]
	global_load_lds_dwordx4 v[242:243], off
	v_lshl_add_u64 v[242:243], s[28:29], 0, v[146:147]
	s_add_i32 m0, s27, 0x2000
	s_nop 0
	global_load_lds_dwordx4 v[242:243], off
	v_lshl_add_u64 v[242:243], s[66:67], 0, v[142:143]
	s_mov_b32 m0, s12
	s_nop 0
	global_load_lds_dwordx4 v[242:243], off
	s_mov_b32 m0, s13
	s_nop 0
	global_load_lds_dwordx4 v[244:245], off
	s_waitcnt vmcnt(8)
	s_waitcnt lgkmcnt(0)
	s_barrier
	s_setprio 1
	s_waitcnt lgkmcnt(0)
	v_mfma_f32_16x16x32_bf16 v[64:67], v[158:161], v[208:211], v[64:67]
	v_mfma_f32_16x16x32_bf16 v[64:67], v[180:183], v[212:215], v[64:67]
	v_mfma_f32_16x16x32_bf16 v[48:51], v[158:161], v[216:219], v[48:51]
	v_mfma_f32_16x16x32_bf16 v[48:51], v[180:183], v[222:225], v[48:51]
	v_mfma_f32_16x16x32_bf16 v[30:33], v[158:161], v[226:229], v[30:33]
	v_mfma_f32_16x16x32_bf16 v[30:33], v[180:183], v[230:233], v[30:33]
	v_mfma_f32_16x16x32_bf16 v[14:17], v[158:161], v[234:237], v[14:17]
	v_mfma_f32_16x16x32_bf16 v[14:17], v[180:183], v[238:241], v[14:17]
	v_mfma_f32_16x16x32_bf16 v[60:63], v[184:187], v[208:211], v[60:63]
	v_mfma_f32_16x16x32_bf16 v[60:63], v[188:191], v[212:215], v[60:63]
	v_mfma_f32_16x16x32_bf16 v[44:47], v[184:187], v[216:219], v[44:47]
	v_mfma_f32_16x16x32_bf16 v[44:47], v[188:191], v[222:225], v[44:47]
	v_mfma_f32_16x16x32_bf16 v[26:29], v[184:187], v[226:229], v[26:29]
	v_mfma_f32_16x16x32_bf16 v[26:29], v[188:191], v[230:233], v[26:29]
	v_mfma_f32_16x16x32_bf16 v[10:13], v[184:187], v[234:237], v[10:13]
	v_mfma_f32_16x16x32_bf16 v[10:13], v[188:191], v[238:241], v[10:13]
	s_setprio 0
	s_setprio 1
	v_mfma_f32_16x16x32_bf16 v[56:59], v[192:195], v[208:211], v[56:59]
	v_mfma_f32_16x16x32_bf16 v[56:59], v[196:199], v[212:215], v[56:59]
	v_mfma_f32_16x16x32_bf16 v[40:43], v[192:195], v[216:219], v[40:43]
	v_mfma_f32_16x16x32_bf16 v[40:43], v[196:199], v[222:225], v[40:43]
	v_mfma_f32_16x16x32_bf16 v[22:25], v[192:195], v[226:229], v[22:25]
	v_mfma_f32_16x16x32_bf16 v[22:25], v[196:199], v[230:233], v[22:25]
	v_mfma_f32_16x16x32_bf16 v[6:9], v[192:195], v[234:237], v[6:9]
	v_mfma_f32_16x16x32_bf16 v[6:9], v[196:199], v[238:241], v[6:9]
	v_mfma_f32_16x16x32_bf16 v[52:55], v[200:203], v[208:211], v[52:55]
	v_mfma_f32_16x16x32_bf16 v[52:55], v[204:207], v[212:215], v[52:55]
	v_mfma_f32_16x16x32_bf16 v[36:39], v[200:203], v[216:219], v[36:39]
	v_mfma_f32_16x16x32_bf16 v[36:39], v[204:207], v[222:225], v[36:39]
	v_mfma_f32_16x16x32_bf16 v[18:21], v[200:203], v[226:229], v[18:21]
	v_mfma_f32_16x16x32_bf16 v[18:21], v[204:207], v[230:233], v[18:21]
	v_mfma_f32_16x16x32_bf16 v[2:5], v[200:203], v[234:237], v[2:5]
	v_mfma_f32_16x16x32_bf16 v[2:5], v[204:207], v[238:241], v[2:5]
	s_setprio 0
	s_barrier
	s_add_i32 s27, 0, 0x18000
	v_add_u32_e32 v157, s27, v154
	s_add_i32 s30, 0, 0x1c000
	ds_read_b128 v[158:161], v157
	ds_read_b128 v[180:183], v157 offset:1024
	ds_read_b128 v[184:187], v157 offset:2048
	ds_read_b128 v[188:191], v157 offset:3072
	v_add_u32_e32 v157, s30, v154
	ds_read_b128 v[192:195], v157
	ds_read_b128 v[196:199], v157 offset:1024
	ds_read_b128 v[200:203], v157 offset:2048
	ds_read_b128 v[204:207], v157 offset:3072
	s_add_u32 s28, s66, 0x80000
	s_addc_u32 s29, s67, 0
	s_mov_b32 m0, s14
	v_lshl_add_u64 v[246:247], s[28:29], 0, v[142:143]
	ds_read_b128 v[208:211], v156 offset:32768
	ds_read_b128 v[212:215], v156 offset:33792
	ds_read_b128 v[216:219], v156 offset:34816
	ds_read_b128 v[222:225], v156 offset:35840
	ds_read_b128 v[226:229], v156 offset:36864
	ds_read_b128 v[230:233], v156 offset:37888
	ds_read_b128 v[234:237], v156 offset:38912
	ds_read_b128 v[238:241], v156 offset:39936
	global_load_lds_dwordx4 v[246:247], off
	v_lshl_add_u64 v[246:247], s[28:29], 0, v[144:145]
	s_mov_b32 m0, s15
	s_nop 0
	global_load_lds_dwordx4 v[246:247], off
	s_waitcnt vmcnt(8)
	s_waitcnt lgkmcnt(0)
	s_barrier
	s_setprio 1
	s_waitcnt lgkmcnt(0)
	v_mfma_f32_16x16x32_bf16 v[128:131], v[158:161], v[208:211], v[128:131]
	v_mfma_f32_16x16x32_bf16 v[128:131], v[180:183], v[212:215], v[128:131]
	v_mfma_f32_16x16x32_bf16 v[112:115], v[158:161], v[216:219], v[112:115]
	v_mfma_f32_16x16x32_bf16 v[112:115], v[180:183], v[222:225], v[112:115]
	v_mfma_f32_16x16x32_bf16 v[96:99], v[158:161], v[226:229], v[96:99]
	v_mfma_f32_16x16x32_bf16 v[96:99], v[180:183], v[230:233], v[96:99]
	v_mfma_f32_16x16x32_bf16 v[80:83], v[158:161], v[234:237], v[80:83]
	v_mfma_f32_16x16x32_bf16 v[80:83], v[180:183], v[238:241], v[80:83]
	v_mfma_f32_16x16x32_bf16 v[124:127], v[184:187], v[208:211], v[124:127]
	v_mfma_f32_16x16x32_bf16 v[124:127], v[188:191], v[212:215], v[124:127]
	v_mfma_f32_16x16x32_bf16 v[108:111], v[184:187], v[216:219], v[108:111]
	v_mfma_f32_16x16x32_bf16 v[108:111], v[188:191], v[222:225], v[108:111]
	v_mfma_f32_16x16x32_bf16 v[92:95], v[184:187], v[226:229], v[92:95]
	v_mfma_f32_16x16x32_bf16 v[92:95], v[188:191], v[230:233], v[92:95]
	v_mfma_f32_16x16x32_bf16 v[76:79], v[184:187], v[234:237], v[76:79]
	v_mfma_f32_16x16x32_bf16 v[76:79], v[188:191], v[238:241], v[76:79]
	s_setprio 0
	s_setprio 1
	v_mfma_f32_16x16x32_bf16 v[120:123], v[192:195], v[208:211], v[120:123]
	v_mfma_f32_16x16x32_bf16 v[120:123], v[196:199], v[212:215], v[120:123]
	v_mfma_f32_16x16x32_bf16 v[104:107], v[192:195], v[216:219], v[104:107]
	v_mfma_f32_16x16x32_bf16 v[104:107], v[196:199], v[222:225], v[104:107]
	v_mfma_f32_16x16x32_bf16 v[88:91], v[192:195], v[226:229], v[88:91]
	v_mfma_f32_16x16x32_bf16 v[88:91], v[196:199], v[230:233], v[88:91]
	v_mfma_f32_16x16x32_bf16 v[72:75], v[192:195], v[234:237], v[72:75]
	v_mfma_f32_16x16x32_bf16 v[72:75], v[196:199], v[238:241], v[72:75]
	v_mfma_f32_16x16x32_bf16 v[116:119], v[200:203], v[208:211], v[116:119]
	v_mfma_f32_16x16x32_bf16 v[116:119], v[204:207], v[212:215], v[116:119]
	v_mfma_f32_16x16x32_bf16 v[100:103], v[200:203], v[216:219], v[100:103]
	v_mfma_f32_16x16x32_bf16 v[100:103], v[204:207], v[222:225], v[100:103]
	v_mfma_f32_16x16x32_bf16 v[84:87], v[200:203], v[226:229], v[84:87]
	v_mfma_f32_16x16x32_bf16 v[84:87], v[204:207], v[230:233], v[84:87]
	v_mfma_f32_16x16x32_bf16 v[68:71], v[200:203], v[234:237], v[68:71]
	v_mfma_f32_16x16x32_bf16 v[68:71], v[204:207], v[238:241], v[68:71]
	s_setprio 0
	s_barrier
	s_add_i32 s27, s27, s11
	v_lshl_add_u64 v[152:153], v[152:153], 0, s[78:79]
	s_mov_b32 m0, s27
	ds_read_b128 v[208:211], v156 offset:49152
	ds_read_b128 v[212:215], v156 offset:50176
	ds_read_b128 v[216:219], v156 offset:51200
	ds_read_b128 v[222:225], v156 offset:52224
	ds_read_b128 v[226:229], v156 offset:53248
	ds_read_b128 v[230:233], v156 offset:54272
	ds_read_b128 v[234:237], v156 offset:55296
	ds_read_b128 v[238:241], v156 offset:56320
	global_load_lds_dwordx4 v[152:153], off
	s_add_i32 m0, s27, 0x2000
	s_add_u32 s28, s54, 0x80080
	v_lshl_add_u64 v[152:153], v[162:163], 0, s[78:79]
	s_addc_u32 s29, s55, 0
	s_add_i32 s27, s30, s11
	global_load_lds_dwordx4 v[152:153], off
	v_lshl_add_u64 v[152:153], s[28:29], 0, v[34:35]
	s_mov_b32 m0, s27
	s_nop 0
	global_load_lds_dwordx4 v[152:153], off
	v_lshl_add_u64 v[152:153], s[28:29], 0, v[146:147]
	s_add_i32 m0, s27, 0x2000
	s_nop 0
	global_load_lds_dwordx4 v[152:153], off
	v_lshl_add_u64 v[152:153], v[242:243], 0, s[78:79]
	s_mov_b32 m0, s16
	s_nop 0
	global_load_lds_dwordx4 v[152:153], off
	v_lshl_add_u64 v[152:153], v[244:245], 0, s[78:79]
	s_mov_b32 m0, s17
	s_nop 0
	global_load_lds_dwordx4 v[152:153], off
	s_waitcnt vmcnt(8)
	s_waitcnt lgkmcnt(0)
	s_barrier
	s_setprio 1
	s_waitcnt lgkmcnt(0)
	v_mfma_f32_16x16x32_bf16 v[64:67], v[158:161], v[208:211], v[64:67]
	v_mfma_f32_16x16x32_bf16 v[64:67], v[180:183], v[212:215], v[64:67]
	v_mfma_f32_16x16x32_bf16 v[48:51], v[158:161], v[216:219], v[48:51]
	v_mfma_f32_16x16x32_bf16 v[48:51], v[180:183], v[222:225], v[48:51]
	v_mfma_f32_16x16x32_bf16 v[30:33], v[158:161], v[226:229], v[30:33]
	v_mfma_f32_16x16x32_bf16 v[30:33], v[180:183], v[230:233], v[30:33]
	v_mfma_f32_16x16x32_bf16 v[14:17], v[158:161], v[234:237], v[14:17]
	v_mfma_f32_16x16x32_bf16 v[14:17], v[180:183], v[238:241], v[14:17]
	v_mfma_f32_16x16x32_bf16 v[60:63], v[184:187], v[208:211], v[60:63]
	v_mfma_f32_16x16x32_bf16 v[60:63], v[188:191], v[212:215], v[60:63]
	v_mfma_f32_16x16x32_bf16 v[44:47], v[184:187], v[216:219], v[44:47]
	v_mfma_f32_16x16x32_bf16 v[44:47], v[188:191], v[222:225], v[44:47]
	v_mfma_f32_16x16x32_bf16 v[26:29], v[184:187], v[226:229], v[26:29]
	v_mfma_f32_16x16x32_bf16 v[26:29], v[188:191], v[230:233], v[26:29]
	v_mfma_f32_16x16x32_bf16 v[10:13], v[184:187], v[234:237], v[10:13]
	v_mfma_f32_16x16x32_bf16 v[10:13], v[188:191], v[238:241], v[10:13]
	s_setprio 0
	s_setprio 1
	v_mfma_f32_16x16x32_bf16 v[56:59], v[192:195], v[208:211], v[56:59]
	v_mfma_f32_16x16x32_bf16 v[56:59], v[196:199], v[212:215], v[56:59]
	v_mfma_f32_16x16x32_bf16 v[40:43], v[192:195], v[216:219], v[40:43]
	v_mfma_f32_16x16x32_bf16 v[40:43], v[196:199], v[222:225], v[40:43]
	v_mfma_f32_16x16x32_bf16 v[22:25], v[192:195], v[226:229], v[22:25]
	v_mfma_f32_16x16x32_bf16 v[22:25], v[196:199], v[230:233], v[22:25]
	v_mfma_f32_16x16x32_bf16 v[6:9], v[192:195], v[234:237], v[6:9]
	v_mfma_f32_16x16x32_bf16 v[6:9], v[196:199], v[238:241], v[6:9]
	v_mfma_f32_16x16x32_bf16 v[52:55], v[200:203], v[208:211], v[52:55]
	v_mfma_f32_16x16x32_bf16 v[52:55], v[204:207], v[212:215], v[52:55]
	v_mfma_f32_16x16x32_bf16 v[36:39], v[200:203], v[216:219], v[36:39]
	v_mfma_f32_16x16x32_bf16 v[36:39], v[204:207], v[222:225], v[36:39]
	v_mfma_f32_16x16x32_bf16 v[18:21], v[200:203], v[226:229], v[18:21]
	v_mfma_f32_16x16x32_bf16 v[18:21], v[204:207], v[230:233], v[18:21]
	v_mfma_f32_16x16x32_bf16 v[2:5], v[200:203], v[234:237], v[2:5]
	v_mfma_f32_16x16x32_bf16 v[2:5], v[204:207], v[238:241], v[2:5]
	s_setprio 0
	s_barrier
	s_add_i32 s26, s26, 2
	s_add_u32 s24, s24, 0x100
	s_addc_u32 s25, s25, 0
	s_add_u32 s62, s62, 0x100
	s_addc_u32 s63, s63, 0
	s_cmp_gt_u32 s26, 29
	s_cbranch_scc0 .LBB0_985
	s_and_b64 vcc, exec, s[36:37]
	s_cbranch_vccz .LBB0_988
	s_barrier

.LBB0_1064:
	s_add_u32 s27, s62, 0xffe00080
	s_addc_u32 s28, s63, -1
	s_add_i32 s29, 0, 0x10000
	s_cmpk_eq_i32 s26, 0x7c
	s_cselect_b32 s67, s20, s28
	s_cselect_b32 s66, s21, s27
	v_add_u32_e32 v152, s29, v154
	s_cselect_b32 s55, s22, s25
	s_cselect_b32 s54, s23, s24
	s_add_i32 s27, 0, 0x14000
	ds_read_b128 v[158:161], v152
	ds_read_b128 v[180:183], v152 offset:1024
	ds_read_b128 v[184:187], v152 offset:2048
	ds_read_b128 v[188:191], v152 offset:3072
	v_add_u32_e32 v152, s27, v154
	ds_read_b128 v[192:195], v152
	ds_read_b128 v[196:199], v152 offset:1024
	ds_read_b128 v[200:203], v152 offset:2048
	ds_read_b128 v[204:207], v152 offset:3072
	v_lshl_add_u64 v[152:153], s[62:63], 0, v[150:151]
	s_add_i32 m0, s12, 0xc000
	ds_read_b128 v[208:211], v156
	ds_read_b128 v[212:215], v156 offset:1024
	ds_read_b128 v[216:219], v156 offset:2048
	ds_read_b128 v[222:225], v156 offset:3072
	ds_read_b128 v[226:229], v156 offset:4096
	ds_read_b128 v[230:233], v156 offset:5120
	ds_read_b128 v[234:237], v156 offset:6144
	ds_read_b128 v[238:241], v156 offset:7168
	global_load_lds_dwordx4 v[152:153], off
	v_lshl_add_u64 v[152:153], s[62:63], 0, v[148:149]
	s_add_i32 m0, s12, 0xe000
	s_nop 0
	global_load_lds_dwordx4 v[152:153], off
	s_waitcnt vmcnt(8)
	s_waitcnt lgkmcnt(0)
	s_barrier
	s_setprio 1
	s_waitcnt lgkmcnt(0)
	v_mfma_f32_16x16x32_bf16 v[128:131], v[158:161], v[208:211], v[128:131]
	v_mfma_f32_16x16x32_bf16 v[128:131], v[180:183], v[212:215], v[128:131]
	v_mfma_f32_16x16x32_bf16 v[120:123], v[158:161], v[216:219], v[120:123]
	v_mfma_f32_16x16x32_bf16 v[120:123], v[180:183], v[222:225], v[120:123]
	v_mfma_f32_16x16x32_bf16 v[104:107], v[158:161], v[226:229], v[104:107]
	v_mfma_f32_16x16x32_bf16 v[104:107], v[180:183], v[230:233], v[104:107]
	v_mfma_f32_16x16x32_bf16 v[88:91], v[158:161], v[234:237], v[88:91]
	v_mfma_f32_16x16x32_bf16 v[88:91], v[180:183], v[238:241], v[88:91]
	v_mfma_f32_16x16x32_bf16 v[124:127], v[184:187], v[208:211], v[124:127]
	v_mfma_f32_16x16x32_bf16 v[124:127], v[188:191], v[212:215], v[124:127]
	v_mfma_f32_16x16x32_bf16 v[112:115], v[184:187], v[216:219], v[112:115]
	v_mfma_f32_16x16x32_bf16 v[112:115], v[188:191], v[222:225], v[112:115]
	v_mfma_f32_16x16x32_bf16 v[96:99], v[184:187], v[226:229], v[96:99]
	v_mfma_f32_16x16x32_bf16 v[96:99], v[188:191], v[230:233], v[96:99]
	v_mfma_f32_16x16x32_bf16 v[80:83], v[184:187], v[234:237], v[80:83]
	v_mfma_f32_16x16x32_bf16 v[80:83], v[188:191], v[238:241], v[80:83]
	s_setprio 0
	s_setprio 1
	v_mfma_f32_16x16x32_bf16 v[116:119], v[192:195], v[208:211], v[116:119]
	v_mfma_f32_16x16x32_bf16 v[116:119], v[196:199], v[212:215], v[116:119]
	v_mfma_f32_16x16x32_bf16 v[100:103], v[192:195], v[216:219], v[100:103]
	v_mfma_f32_16x16x32_bf16 v[100:103], v[196:199], v[222:225], v[100:103]
	v_mfma_f32_16x16x32_bf16 v[84:87], v[192:195], v[226:229], v[84:87]
	v_mfma_f32_16x16x32_bf16 v[84:87], v[196:199], v[230:233], v[84:87]
	v_mfma_f32_16x16x32_bf16 v[72:75], v[192:195], v[234:237], v[72:75]
	v_mfma_f32_16x16x32_bf16 v[72:75], v[196:199], v[238:241], v[72:75]
	v_mfma_f32_16x16x32_bf16 v[108:111], v[200:203], v[208:211], v[108:111]
	v_mfma_f32_16x16x32_bf16 v[108:111], v[204:207], v[212:215], v[108:111]
	v_mfma_f32_16x16x32_bf16 v[92:95], v[200:203], v[216:219], v[92:95]
	v_mfma_f32_16x16x32_bf16 v[92:95], v[204:207], v[222:225], v[92:95]
	v_mfma_f32_16x16x32_bf16 v[76:79], v[200:203], v[226:229], v[76:79]
	v_mfma_f32_16x16x32_bf16 v[76:79], v[204:207], v[230:233], v[76:79]
	v_mfma_f32_16x16x32_bf16 v[68:71], v[200:203], v[234:237], v[68:71]
	v_mfma_f32_16x16x32_bf16 v[68:71], v[204:207], v[238:241], v[68:71]
	s_setprio 0
	s_barrier
	s_add_i32 s28, s29, s11
	v_lshl_add_u64 v[152:153], s[54:55], 0, v[34:35]
	s_mov_b32 m0, s28
	ds_read_b128 v[208:211], v156 offset:16384
	ds_read_b128 v[212:215], v156 offset:17408
	ds_read_b128 v[216:219], v156 offset:18432
	ds_read_b128 v[222:225], v156 offset:19456
	ds_read_b128 v[226:229], v156 offset:20480
	ds_read_b128 v[230:233], v156 offset:21504
	ds_read_b128 v[234:237], v156 offset:22528
	ds_read_b128 v[238:241], v156 offset:23552
	global_load_lds_dwordx4 v[152:153], off
	s_add_i32 m0, s28, 0x2000
	s_add_u32 s28, s54, 0x200000
	v_lshl_add_u64 v[162:163], s[54:55], 0, v[146:147]
	s_addc_u32 s29, s55, 0
	s_add_i32 s27, s27, s11
	global_load_lds_dwordx4 v[162:163], off
	v_lshl_add_u64 v[242:243], s[28:29], 0, v[34:35]
	s_mov_b32 m0, s27
	v_lshl_add_u64 v[244:245], s[66:67], 0, v[144:145]
	global_load_lds_dwordx4 v[242:243], off
	v_lshl_add_u64 v[242:243], s[28:29], 0, v[146:147]
	s_add_i32 m0, s27, 0x2000
	s_nop 0
	global_load_lds_dwordx4 v[242:243], off
	v_lshl_add_u64 v[242:243], s[66:67], 0, v[142:143]
	s_mov_b32 m0, s12
	s_nop 0
	global_load_lds_dwordx4 v[242:243], off
	s_mov_b32 m0, s13
	s_nop 0
	global_load_lds_dwordx4 v[244:245], off
	s_waitcnt vmcnt(8)
	s_waitcnt lgkmcnt(0)
	s_barrier
	s_setprio 1
	s_waitcnt lgkmcnt(0)
	v_mfma_f32_16x16x32_bf16 v[64:67], v[158:161], v[208:211], v[64:67]
	v_mfma_f32_16x16x32_bf16 v[64:67], v[180:183], v[212:215], v[64:67]
	v_mfma_f32_16x16x32_bf16 v[56:59], v[158:161], v[216:219], v[56:59]
	v_mfma_f32_16x16x32_bf16 v[56:59], v[180:183], v[222:225], v[56:59]
	v_mfma_f32_16x16x32_bf16 v[40:43], v[158:161], v[226:229], v[40:43]
	v_mfma_f32_16x16x32_bf16 v[40:43], v[180:183], v[230:233], v[40:43]
	v_mfma_f32_16x16x32_bf16 v[22:25], v[158:161], v[234:237], v[22:25]
	v_mfma_f32_16x16x32_bf16 v[22:25], v[180:183], v[238:241], v[22:25]
	v_mfma_f32_16x16x32_bf16 v[60:63], v[184:187], v[208:211], v[60:63]
	v_mfma_f32_16x16x32_bf16 v[60:63], v[188:191], v[212:215], v[60:63]
	v_mfma_f32_16x16x32_bf16 v[48:51], v[184:187], v[216:219], v[48:51]
	v_mfma_f32_16x16x32_bf16 v[48:51], v[188:191], v[222:225], v[48:51]
	v_mfma_f32_16x16x32_bf16 v[30:33], v[184:187], v[226:229], v[30:33]
	v_mfma_f32_16x16x32_bf16 v[30:33], v[188:191], v[230:233], v[30:33]
	v_mfma_f32_16x16x32_bf16 v[14:17], v[184:187], v[234:237], v[14:17]
	v_mfma_f32_16x16x32_bf16 v[14:17], v[188:191], v[238:241], v[14:17]
	s_setprio 0
	s_setprio 1
	v_mfma_f32_16x16x32_bf16 v[52:55], v[192:195], v[208:211], v[52:55]
	v_mfma_f32_16x16x32_bf16 v[52:55], v[196:199], v[212:215], v[52:55]
	v_mfma_f32_16x16x32_bf16 v[36:39], v[192:195], v[216:219], v[36:39]
	v_mfma_f32_16x16x32_bf16 v[36:39], v[196:199], v[222:225], v[36:39]
	v_mfma_f32_16x16x32_bf16 v[18:21], v[192:195], v[226:229], v[18:21]
	v_mfma_f32_16x16x32_bf16 v[18:21], v[196:199], v[230:233], v[18:21]
	v_mfma_f32_16x16x32_bf16 v[6:9], v[192:195], v[234:237], v[6:9]
	v_mfma_f32_16x16x32_bf16 v[6:9], v[196:199], v[238:241], v[6:9]
	v_mfma_f32_16x16x32_bf16 v[44:47], v[200:203], v[208:211], v[44:47]
	v_mfma_f32_16x16x32_bf16 v[44:47], v[204:207], v[212:215], v[44:47]
	v_mfma_f32_16x16x32_bf16 v[26:29], v[200:203], v[216:219], v[26:29]
	v_mfma_f32_16x16x32_bf16 v[26:29], v[204:207], v[222:225], v[26:29]
	v_mfma_f32_16x16x32_bf16 v[10:13], v[200:203], v[226:229], v[10:13]
	v_mfma_f32_16x16x32_bf16 v[10:13], v[204:207], v[230:233], v[10:13]
	v_mfma_f32_16x16x32_bf16 v[2:5], v[200:203], v[234:237], v[2:5]
	v_mfma_f32_16x16x32_bf16 v[2:5], v[204:207], v[238:241], v[2:5]
	s_setprio 0
	s_barrier
	s_add_i32 s27, 0, 0x18000
	v_add_u32_e32 v157, s27, v154
	s_add_i32 s30, 0, 0x1c000
	ds_read_b128 v[158:161], v157
	ds_read_b128 v[180:183], v157 offset:1024
	ds_read_b128 v[184:187], v157 offset:2048
	ds_read_b128 v[188:191], v157 offset:3072
	v_add_u32_e32 v157, s30, v154
	ds_read_b128 v[192:195], v157
	ds_read_b128 v[196:199], v157 offset:1024
	ds_read_b128 v[200:203], v157 offset:2048
	ds_read_b128 v[204:207], v157 offset:3072
	s_add_u32 s28, s66, 0x200000
	s_addc_u32 s29, s67, 0
	s_mov_b32 m0, s14
	v_lshl_add_u64 v[246:247], s[28:29], 0, v[142:143]
	ds_read_b128 v[208:211], v156 offset:32768
	ds_read_b128 v[212:215], v156 offset:33792
	ds_read_b128 v[216:219], v156 offset:34816
	ds_read_b128 v[222:225], v156 offset:35840
	ds_read_b128 v[226:229], v156 offset:36864
	ds_read_b128 v[230:233], v156 offset:37888
	ds_read_b128 v[234:237], v156 offset:38912
	ds_read_b128 v[238:241], v156 offset:39936
	global_load_lds_dwordx4 v[246:247], off
	v_lshl_add_u64 v[246:247], s[28:29], 0, v[144:145]
	s_mov_b32 m0, s15
	s_nop 0
	global_load_lds_dwordx4 v[246:247], off
	s_waitcnt vmcnt(8)
	s_waitcnt lgkmcnt(0)
	s_barrier
	s_setprio 1
	s_waitcnt lgkmcnt(0)
	v_mfma_f32_16x16x32_bf16 v[128:131], v[158:161], v[208:211], v[128:131]
	v_mfma_f32_16x16x32_bf16 v[128:131], v[180:183], v[212:215], v[128:131]
	v_mfma_f32_16x16x32_bf16 v[120:123], v[158:161], v[216:219], v[120:123]
	v_mfma_f32_16x16x32_bf16 v[120:123], v[180:183], v[222:225], v[120:123]
	v_mfma_f32_16x16x32_bf16 v[104:107], v[158:161], v[226:229], v[104:107]
	v_mfma_f32_16x16x32_bf16 v[104:107], v[180:183], v[230:233], v[104:107]
	v_mfma_f32_16x16x32_bf16 v[88:91], v[158:161], v[234:237], v[88:91]
	v_mfma_f32_16x16x32_bf16 v[88:91], v[180:183], v[238:241], v[88:91]
	v_mfma_f32_16x16x32_bf16 v[124:127], v[184:187], v[208:211], v[124:127]
	v_mfma_f32_16x16x32_bf16 v[124:127], v[188:191], v[212:215], v[124:127]
	v_mfma_f32_16x16x32_bf16 v[112:115], v[184:187], v[216:219], v[112:115]
	v_mfma_f32_16x16x32_bf16 v[112:115], v[188:191], v[222:225], v[112:115]
	v_mfma_f32_16x16x32_bf16 v[96:99], v[184:187], v[226:229], v[96:99]
	v_mfma_f32_16x16x32_bf16 v[96:99], v[188:191], v[230:233], v[96:99]
	v_mfma_f32_16x16x32_bf16 v[80:83], v[184:187], v[234:237], v[80:83]
	v_mfma_f32_16x16x32_bf16 v[80:83], v[188:191], v[238:241], v[80:83]
	s_setprio 0
	s_setprio 1
	v_mfma_f32_16x16x32_bf16 v[116:119], v[192:195], v[208:211], v[116:119]
	v_mfma_f32_16x16x32_bf16 v[116:119], v[196:199], v[212:215], v[116:119]
	v_mfma_f32_16x16x32_bf16 v[100:103], v[192:195], v[216:219], v[100:103]
	v_mfma_f32_16x16x32_bf16 v[100:103], v[196:199], v[222:225], v[100:103]
	v_mfma_f32_16x16x32_bf16 v[84:87], v[192:195], v[226:229], v[84:87]
	v_mfma_f32_16x16x32_bf16 v[84:87], v[196:199], v[230:233], v[84:87]
	v_mfma_f32_16x16x32_bf16 v[72:75], v[192:195], v[234:237], v[72:75]
	v_mfma_f32_16x16x32_bf16 v[72:75], v[196:199], v[238:241], v[72:75]
	v_mfma_f32_16x16x32_bf16 v[108:111], v[200:203], v[208:211], v[108:111]
	v_mfma_f32_16x16x32_bf16 v[108:111], v[204:207], v[212:215], v[108:111]
	v_mfma_f32_16x16x32_bf16 v[92:95], v[200:203], v[216:219], v[92:95]
	v_mfma_f32_16x16x32_bf16 v[92:95], v[204:207], v[222:225], v[92:95]
	v_mfma_f32_16x16x32_bf16 v[76:79], v[200:203], v[226:229], v[76:79]
	v_mfma_f32_16x16x32_bf16 v[76:79], v[204:207], v[230:233], v[76:79]
	v_mfma_f32_16x16x32_bf16 v[68:71], v[200:203], v[234:237], v[68:71]
	v_mfma_f32_16x16x32_bf16 v[68:71], v[204:207], v[238:241], v[68:71]
	s_setprio 0
	s_barrier
	s_add_i32 s27, s27, s11
	v_lshl_add_u64 v[152:153], v[152:153], 0, s[78:79]
	s_mov_b32 m0, s27
	ds_read_b128 v[208:211], v156 offset:49152
	ds_read_b128 v[212:215], v156 offset:50176
	ds_read_b128 v[216:219], v156 offset:51200
	ds_read_b128 v[222:225], v156 offset:52224
	ds_read_b128 v[226:229], v156 offset:53248
	ds_read_b128 v[230:233], v156 offset:54272
	ds_read_b128 v[234:237], v156 offset:55296
	ds_read_b128 v[238:241], v156 offset:56320
	global_load_lds_dwordx4 v[152:153], off
	s_add_i32 m0, s27, 0x2000
	s_add_u32 s28, s54, 0x200080
	v_lshl_add_u64 v[152:153], v[162:163], 0, s[78:79]
	s_addc_u32 s29, s55, 0
	s_add_i32 s27, s30, s11
	global_load_lds_dwordx4 v[152:153], off
	v_lshl_add_u64 v[152:153], s[28:29], 0, v[34:35]
	s_mov_b32 m0, s27
	s_nop 0
	global_load_lds_dwordx4 v[152:153], off
	v_lshl_add_u64 v[152:153], s[28:29], 0, v[146:147]
	s_add_i32 m0, s27, 0x2000
	s_nop 0
	global_load_lds_dwordx4 v[152:153], off
	v_lshl_add_u64 v[152:153], v[242:243], 0, s[78:79]
	s_mov_b32 m0, s16
	s_nop 0
	global_load_lds_dwordx4 v[152:153], off
	v_lshl_add_u64 v[152:153], v[244:245], 0, s[78:79]
	s_mov_b32 m0, s17
	s_nop 0
	global_load_lds_dwordx4 v[152:153], off
	s_waitcnt vmcnt(8)
	s_waitcnt lgkmcnt(0)
	s_barrier
	s_setprio 1
	s_waitcnt lgkmcnt(0)
	v_mfma_f32_16x16x32_bf16 v[64:67], v[158:161], v[208:211], v[64:67]
	v_mfma_f32_16x16x32_bf16 v[64:67], v[180:183], v[212:215], v[64:67]
	v_mfma_f32_16x16x32_bf16 v[56:59], v[158:161], v[216:219], v[56:59]
	v_mfma_f32_16x16x32_bf16 v[56:59], v[180:183], v[222:225], v[56:59]
	v_mfma_f32_16x16x32_bf16 v[40:43], v[158:161], v[226:229], v[40:43]
	v_mfma_f32_16x16x32_bf16 v[40:43], v[180:183], v[230:233], v[40:43]
	v_mfma_f32_16x16x32_bf16 v[22:25], v[158:161], v[234:237], v[22:25]
	v_mfma_f32_16x16x32_bf16 v[22:25], v[180:183], v[238:241], v[22:25]
	v_mfma_f32_16x16x32_bf16 v[60:63], v[184:187], v[208:211], v[60:63]
	v_mfma_f32_16x16x32_bf16 v[60:63], v[188:191], v[212:215], v[60:63]
	v_mfma_f32_16x16x32_bf16 v[48:51], v[184:187], v[216:219], v[48:51]
	v_mfma_f32_16x16x32_bf16 v[48:51], v[188:191], v[222:225], v[48:51]
	v_mfma_f32_16x16x32_bf16 v[30:33], v[184:187], v[226:229], v[30:33]
	v_mfma_f32_16x16x32_bf16 v[30:33], v[188:191], v[230:233], v[30:33]
	v_mfma_f32_16x16x32_bf16 v[14:17], v[184:187], v[234:237], v[14:17]
	v_mfma_f32_16x16x32_bf16 v[14:17], v[188:191], v[238:241], v[14:17]
	s_setprio 0
	s_setprio 1
	v_mfma_f32_16x16x32_bf16 v[52:55], v[192:195], v[208:211], v[52:55]
	v_mfma_f32_16x16x32_bf16 v[52:55], v[196:199], v[212:215], v[52:55]
	v_mfma_f32_16x16x32_bf16 v[36:39], v[192:195], v[216:219], v[36:39]
	v_mfma_f32_16x16x32_bf16 v[36:39], v[196:199], v[222:225], v[36:39]
	v_mfma_f32_16x16x32_bf16 v[18:21], v[192:195], v[226:229], v[18:21]
	v_mfma_f32_16x16x32_bf16 v[18:21], v[196:199], v[230:233], v[18:21]
	v_mfma_f32_16x16x32_bf16 v[6:9], v[192:195], v[234:237], v[6:9]
	v_mfma_f32_16x16x32_bf16 v[6:9], v[196:199], v[238:241], v[6:9]
	v_mfma_f32_16x16x32_bf16 v[44:47], v[200:203], v[208:211], v[44:47]
	v_mfma_f32_16x16x32_bf16 v[44:47], v[204:207], v[212:215], v[44:47]
	v_mfma_f32_16x16x32_bf16 v[26:29], v[200:203], v[216:219], v[26:29]
	v_mfma_f32_16x16x32_bf16 v[26:29], v[204:207], v[222:225], v[26:29]
	v_mfma_f32_16x16x32_bf16 v[10:13], v[200:203], v[226:229], v[10:13]
	v_mfma_f32_16x16x32_bf16 v[10:13], v[204:207], v[230:233], v[10:13]
	v_mfma_f32_16x16x32_bf16 v[2:5], v[200:203], v[234:237], v[2:5]
	v_mfma_f32_16x16x32_bf16 v[2:5], v[204:207], v[238:241], v[2:5]
	s_setprio 0
	s_barrier
	s_add_i32 s26, s26, 2
	s_add_u32 s24, s24, 0x100
	s_addc_u32 s25, s25, 0
	s_add_u32 s62, s62, 0x100
	s_addc_u32 s63, s63, 0
	s_cmpk_gt_u32 s26, 0x7d
	s_cbranch_scc0 .LBB0_1064
	s_and_b64 vcc, exec, s[44:45]
	s_cbranch_vccz .LBB0_1067
	s_barrier

.LBB0_1207:
	s_add_u32 s30, s90, 0xfff80080
	s_addc_u32 s31, s91, -1
	s_add_i32 s40, 0, 0x10000
	s_cmp_eq_u32 s29, 28
	s_cselect_b32 vcc_hi, s23, s31
	s_cselect_b32 vcc_lo, s24, s30
	v_add_u32_e32 v142, s40, v146
	s_cselect_b32 s55, s25, s28
	s_cselect_b32 s54, s26, s27
	s_add_i32 s44, 0, 0x14000
	ds_read_b128 v[150:153], v142
	ds_read_b128 v[154:157], v142 offset:1024
	ds_read_b128 v[158:161], v142 offset:2048
	ds_read_b128 v[162:165], v142 offset:3072
	v_add_u32_e32 v142, s44, v146
	ds_read_b128 v[166:169], v142
	ds_read_b128 v[170:173], v142 offset:1024
	ds_read_b128 v[174:177], v142 offset:2048
	ds_read_b128 v[178:181], v142 offset:3072
	v_lshl_add_u64 v[144:145], s[90:91], 0, v[138:139]
	s_add_i32 m0, s15, 0xc000
	ds_read_b128 v[182:185], v148
	ds_read_b128 v[186:189], v148 offset:1024
	ds_read_b128 v[190:193], v148 offset:2048
	ds_read_b128 v[210:213], v148 offset:3072
	ds_read_b128 v[214:217], v148 offset:4096
	ds_read_b128 v[230:233], v148 offset:5120
	ds_read_b128 v[234:237], v148 offset:6144
	ds_read_b128 v[238:241], v148 offset:7168
	global_load_lds_dwordx4 v[144:145], off
	v_lshl_add_u64 v[144:145], s[90:91], 0, v[136:137]
	s_add_i32 m0, s15, 0xe000
	s_nop 0
	global_load_lds_dwordx4 v[144:145], off
	s_waitcnt vmcnt(8)
	s_waitcnt lgkmcnt(0)
	s_barrier
	s_setprio 1
	s_waitcnt lgkmcnt(0)
	v_mfma_f32_16x16x32_bf16 v[126:129], v[150:153], v[182:185], v[126:129]
	v_mfma_f32_16x16x32_bf16 v[126:129], v[154:157], v[186:189], v[126:129]
	v_mfma_f32_16x16x32_bf16 v[114:117], v[150:153], v[190:193], v[114:117]
	v_mfma_f32_16x16x32_bf16 v[114:117], v[154:157], v[210:213], v[114:117]
	v_mfma_f32_16x16x32_bf16 v[98:101], v[150:153], v[214:217], v[98:101]
	v_mfma_f32_16x16x32_bf16 v[98:101], v[154:157], v[230:233], v[98:101]
	v_mfma_f32_16x16x32_bf16 v[82:85], v[150:153], v[234:237], v[82:85]
	v_mfma_f32_16x16x32_bf16 v[82:85], v[154:157], v[238:241], v[82:85]
	v_mfma_f32_16x16x32_bf16 v[122:125], v[158:161], v[182:185], v[122:125]
	v_mfma_f32_16x16x32_bf16 v[122:125], v[162:165], v[186:189], v[122:125]
	v_mfma_f32_16x16x32_bf16 v[106:109], v[158:161], v[190:193], v[106:109]
	v_mfma_f32_16x16x32_bf16 v[106:109], v[162:165], v[210:213], v[106:109]
	v_mfma_f32_16x16x32_bf16 v[90:93], v[158:161], v[214:217], v[90:93]
	v_mfma_f32_16x16x32_bf16 v[90:93], v[162:165], v[230:233], v[90:93]
	v_mfma_f32_16x16x32_bf16 v[74:77], v[158:161], v[234:237], v[74:77]
	v_mfma_f32_16x16x32_bf16 v[74:77], v[162:165], v[238:241], v[74:77]
	s_setprio 0
	s_setprio 1
	v_mfma_f32_16x16x32_bf16 v[118:121], v[166:169], v[182:185], v[118:121]
	v_mfma_f32_16x16x32_bf16 v[118:121], v[170:173], v[186:189], v[118:121]
	v_mfma_f32_16x16x32_bf16 v[102:105], v[166:169], v[190:193], v[102:105]
	v_mfma_f32_16x16x32_bf16 v[102:105], v[170:173], v[210:213], v[102:105]
	v_mfma_f32_16x16x32_bf16 v[86:89], v[166:169], v[214:217], v[86:89]
	v_mfma_f32_16x16x32_bf16 v[86:89], v[170:173], v[230:233], v[86:89]
	v_mfma_f32_16x16x32_bf16 v[70:73], v[166:169], v[234:237], v[70:73]
	v_mfma_f32_16x16x32_bf16 v[70:73], v[170:173], v[238:241], v[70:73]
	v_mfma_f32_16x16x32_bf16 v[110:113], v[174:177], v[182:185], v[110:113]
	v_mfma_f32_16x16x32_bf16 v[110:113], v[178:181], v[186:189], v[110:113]
	v_mfma_f32_16x16x32_bf16 v[94:97], v[174:177], v[190:193], v[94:97]
	v_mfma_f32_16x16x32_bf16 v[94:97], v[178:181], v[210:213], v[94:97]
	v_mfma_f32_16x16x32_bf16 v[78:81], v[174:177], v[214:217], v[78:81]
	v_mfma_f32_16x16x32_bf16 v[78:81], v[178:181], v[230:233], v[78:81]
	v_mfma_f32_16x16x32_bf16 v[66:69], v[174:177], v[234:237], v[66:69]
	v_mfma_f32_16x16x32_bf16 v[66:69], v[178:181], v[238:241], v[66:69]
	s_setprio 0
	s_barrier
	s_add_i32 s30, s40, s10
	v_lshl_add_u64 v[144:145], s[54:55], 0, v[194:195]
	s_mov_b32 m0, s30
	ds_read_b128 v[182:185], v148 offset:16384
	ds_read_b128 v[186:189], v148 offset:17408
	ds_read_b128 v[190:193], v148 offset:18432
	ds_read_b128 v[210:213], v148 offset:19456
	ds_read_b128 v[214:217], v148 offset:20480
	ds_read_b128 v[230:233], v148 offset:21504
	ds_read_b128 v[234:237], v148 offset:22528
	ds_read_b128 v[238:241], v148 offset:23552
	global_load_lds_dwordx4 v[144:145], off
	s_add_i32 m0, s30, 0x2000
	s_add_u32 s30, s54, 0x80000
	v_lshl_add_u64 v[218:219], s[54:55], 0, v[130:131]
	s_addc_u32 s31, s55, 0
	s_add_i32 s40, s44, s10
	global_load_lds_dwordx4 v[218:219], off
	v_lshl_add_u64 v[242:243], s[30:31], 0, v[194:195]
	s_mov_b32 m0, s40
	v_lshl_add_u64 v[244:245], vcc, 0, v[132:133]
	global_load_lds_dwordx4 v[242:243], off
	v_lshl_add_u64 v[242:243], s[30:31], 0, v[130:131]
	s_add_i32 m0, s40, 0x2000
	s_nop 0
	global_load_lds_dwordx4 v[242:243], off
	v_lshl_add_u64 v[242:243], vcc, 0, v[134:135]
	s_mov_b32 m0, s15
	s_nop 0
	global_load_lds_dwordx4 v[242:243], off
	s_mov_b32 m0, s16
	s_nop 0
	global_load_lds_dwordx4 v[244:245], off
	s_waitcnt vmcnt(8)
	s_waitcnt lgkmcnt(0)
	s_barrier
	s_setprio 1
	s_waitcnt lgkmcnt(0)
	v_mfma_f32_16x16x32_bf16 v[62:65], v[150:153], v[182:185], v[62:65]
	v_mfma_f32_16x16x32_bf16 v[62:65], v[154:157], v[186:189], v[62:65]
	v_mfma_f32_16x16x32_bf16 v[50:53], v[150:153], v[190:193], v[50:53]
	v_mfma_f32_16x16x32_bf16 v[50:53], v[154:157], v[210:213], v[50:53]
	v_mfma_f32_16x16x32_bf16 v[34:37], v[150:153], v[214:217], v[34:37]
	v_mfma_f32_16x16x32_bf16 v[34:37], v[154:157], v[230:233], v[34:37]
	v_mfma_f32_16x16x32_bf16 v[18:21], v[150:153], v[234:237], v[18:21]
	v_mfma_f32_16x16x32_bf16 v[18:21], v[154:157], v[238:241], v[18:21]
	v_mfma_f32_16x16x32_bf16 v[58:61], v[158:161], v[182:185], v[58:61]
	v_mfma_f32_16x16x32_bf16 v[58:61], v[162:165], v[186:189], v[58:61]
	v_mfma_f32_16x16x32_bf16 v[42:45], v[158:161], v[190:193], v[42:45]
	v_mfma_f32_16x16x32_bf16 v[42:45], v[162:165], v[210:213], v[42:45]
	v_mfma_f32_16x16x32_bf16 v[26:29], v[158:161], v[214:217], v[26:29]
	v_mfma_f32_16x16x32_bf16 v[26:29], v[162:165], v[230:233], v[26:29]
	v_mfma_f32_16x16x32_bf16 v[10:13], v[158:161], v[234:237], v[10:13]
	v_mfma_f32_16x16x32_bf16 v[10:13], v[162:165], v[238:241], v[10:13]
	s_setprio 0
	s_setprio 1
	v_mfma_f32_16x16x32_bf16 v[54:57], v[166:169], v[182:185], v[54:57]
	v_mfma_f32_16x16x32_bf16 v[54:57], v[170:173], v[186:189], v[54:57]
	v_mfma_f32_16x16x32_bf16 v[38:41], v[166:169], v[190:193], v[38:41]
	v_mfma_f32_16x16x32_bf16 v[38:41], v[170:173], v[210:213], v[38:41]
	v_mfma_f32_16x16x32_bf16 v[22:25], v[166:169], v[214:217], v[22:25]
	v_mfma_f32_16x16x32_bf16 v[22:25], v[170:173], v[230:233], v[22:25]
	v_mfma_f32_16x16x32_bf16 v[6:9], v[166:169], v[234:237], v[6:9]
	v_mfma_f32_16x16x32_bf16 v[6:9], v[170:173], v[238:241], v[6:9]
	v_mfma_f32_16x16x32_bf16 v[46:49], v[174:177], v[182:185], v[46:49]
	v_mfma_f32_16x16x32_bf16 v[46:49], v[178:181], v[186:189], v[46:49]
	v_mfma_f32_16x16x32_bf16 v[30:33], v[174:177], v[190:193], v[30:33]
	v_mfma_f32_16x16x32_bf16 v[30:33], v[178:181], v[210:213], v[30:33]
	v_mfma_f32_16x16x32_bf16 v[14:17], v[174:177], v[214:217], v[14:17]
	v_mfma_f32_16x16x32_bf16 v[14:17], v[178:181], v[230:233], v[14:17]
	v_mfma_f32_16x16x32_bf16 v[2:5], v[174:177], v[234:237], v[2:5]
	v_mfma_f32_16x16x32_bf16 v[2:5], v[178:181], v[238:241], v[2:5]
	s_setprio 0
	s_barrier
	s_add_i32 s40, 0, 0x18000
	v_add_u32_e32 v142, s40, v146
	s_add_i32 s44, 0, 0x1c000
	ds_read_b128 v[150:153], v142
	ds_read_b128 v[154:157], v142 offset:1024
	ds_read_b128 v[158:161], v142 offset:2048
	ds_read_b128 v[162:165], v142 offset:3072
	v_add_u32_e32 v142, s44, v146
	ds_read_b128 v[166:169], v142
	ds_read_b128 v[170:173], v142 offset:1024
	ds_read_b128 v[174:177], v142 offset:2048
	ds_read_b128 v[178:181], v142 offset:3072
	s_add_u32 s30, vcc_lo, 0x80000
	s_addc_u32 s31, vcc_hi, 0
	s_mov_b32 m0, s17
	v_lshl_add_u64 v[246:247], s[30:31], 0, v[134:135]
	ds_read_b128 v[182:185], v148 offset:32768
	ds_read_b128 v[186:189], v148 offset:33792
	ds_read_b128 v[190:193], v148 offset:34816
	ds_read_b128 v[210:213], v148 offset:35840
	ds_read_b128 v[214:217], v148 offset:36864
	ds_read_b128 v[230:233], v148 offset:37888
	ds_read_b128 v[234:237], v148 offset:38912
	ds_read_b128 v[238:241], v148 offset:39936
	global_load_lds_dwordx4 v[246:247], off
	v_lshl_add_u64 v[246:247], s[30:31], 0, v[132:133]
	s_mov_b32 m0, s18
	s_nop 0
	global_load_lds_dwordx4 v[246:247], off
	s_waitcnt vmcnt(8)
	s_waitcnt lgkmcnt(0)
	s_barrier
	s_setprio 1
	s_waitcnt lgkmcnt(0)
	v_mfma_f32_16x16x32_bf16 v[126:129], v[150:153], v[182:185], v[126:129]
	v_mfma_f32_16x16x32_bf16 v[126:129], v[154:157], v[186:189], v[126:129]
	v_mfma_f32_16x16x32_bf16 v[114:117], v[150:153], v[190:193], v[114:117]
	v_mfma_f32_16x16x32_bf16 v[114:117], v[154:157], v[210:213], v[114:117]
	v_mfma_f32_16x16x32_bf16 v[98:101], v[150:153], v[214:217], v[98:101]
	v_mfma_f32_16x16x32_bf16 v[98:101], v[154:157], v[230:233], v[98:101]
	v_mfma_f32_16x16x32_bf16 v[82:85], v[150:153], v[234:237], v[82:85]
	v_mfma_f32_16x16x32_bf16 v[82:85], v[154:157], v[238:241], v[82:85]
	v_mfma_f32_16x16x32_bf16 v[122:125], v[158:161], v[182:185], v[122:125]
	v_mfma_f32_16x16x32_bf16 v[122:125], v[162:165], v[186:189], v[122:125]
	v_mfma_f32_16x16x32_bf16 v[106:109], v[158:161], v[190:193], v[106:109]
	v_mfma_f32_16x16x32_bf16 v[106:109], v[162:165], v[210:213], v[106:109]
	v_mfma_f32_16x16x32_bf16 v[90:93], v[158:161], v[214:217], v[90:93]
	v_mfma_f32_16x16x32_bf16 v[90:93], v[162:165], v[230:233], v[90:93]
	v_mfma_f32_16x16x32_bf16 v[74:77], v[158:161], v[234:237], v[74:77]
	v_mfma_f32_16x16x32_bf16 v[74:77], v[162:165], v[238:241], v[74:77]
	s_setprio 0
	s_setprio 1
	v_mfma_f32_16x16x32_bf16 v[118:121], v[166:169], v[182:185], v[118:121]
	v_mfma_f32_16x16x32_bf16 v[118:121], v[170:173], v[186:189], v[118:121]
	v_mfma_f32_16x16x32_bf16 v[102:105], v[166:169], v[190:193], v[102:105]
	v_mfma_f32_16x16x32_bf16 v[102:105], v[170:173], v[210:213], v[102:105]
	v_mfma_f32_16x16x32_bf16 v[86:89], v[166:169], v[214:217], v[86:89]
	v_mfma_f32_16x16x32_bf16 v[86:89], v[170:173], v[230:233], v[86:89]
	v_mfma_f32_16x16x32_bf16 v[70:73], v[166:169], v[234:237], v[70:73]
	v_mfma_f32_16x16x32_bf16 v[70:73], v[170:173], v[238:241], v[70:73]
	v_mfma_f32_16x16x32_bf16 v[110:113], v[174:177], v[182:185], v[110:113]
	v_mfma_f32_16x16x32_bf16 v[110:113], v[178:181], v[186:189], v[110:113]
	v_mfma_f32_16x16x32_bf16 v[94:97], v[174:177], v[190:193], v[94:97]
	v_mfma_f32_16x16x32_bf16 v[94:97], v[178:181], v[210:213], v[94:97]
	v_mfma_f32_16x16x32_bf16 v[78:81], v[174:177], v[214:217], v[78:81]
	v_mfma_f32_16x16x32_bf16 v[78:81], v[178:181], v[230:233], v[78:81]
	v_mfma_f32_16x16x32_bf16 v[66:69], v[174:177], v[234:237], v[66:69]
	v_mfma_f32_16x16x32_bf16 v[66:69], v[178:181], v[238:241], v[66:69]
	s_setprio 0
	s_barrier
	s_add_i32 s30, s40, s10
	v_lshl_add_u64 v[144:145], v[144:145], 0, s[56:57]
	s_mov_b32 m0, s30
	ds_read_b128 v[182:185], v148 offset:49152
	ds_read_b128 v[186:189], v148 offset:50176
	ds_read_b128 v[190:193], v148 offset:51200
	ds_read_b128 v[210:213], v148 offset:52224
	ds_read_b128 v[214:217], v148 offset:53248
	ds_read_b128 v[230:233], v148 offset:54272
	ds_read_b128 v[234:237], v148 offset:55296
	ds_read_b128 v[238:241], v148 offset:56320
	global_load_lds_dwordx4 v[144:145], off
	s_add_i32 m0, s30, 0x2000
	s_add_u32 s30, s54, 0x80080
	v_lshl_add_u64 v[144:145], v[218:219], 0, s[56:57]
	s_addc_u32 s31, s55, 0
	s_add_i32 s40, s44, s10
	global_load_lds_dwordx4 v[144:145], off
	v_lshl_add_u64 v[144:145], s[30:31], 0, v[194:195]
	s_mov_b32 m0, s40
	s_nop 0
	global_load_lds_dwordx4 v[144:145], off
	v_lshl_add_u64 v[144:145], s[30:31], 0, v[130:131]
	s_add_i32 m0, s40, 0x2000
	s_nop 0
	global_load_lds_dwordx4 v[144:145], off
	v_lshl_add_u64 v[144:145], v[242:243], 0, s[56:57]
	s_mov_b32 m0, s21
	s_nop 0
	global_load_lds_dwordx4 v[144:145], off
	v_lshl_add_u64 v[144:145], v[244:245], 0, s[56:57]
	s_mov_b32 m0, s22
	s_nop 0
	global_load_lds_dwordx4 v[144:145], off
	s_waitcnt vmcnt(8)
	s_waitcnt lgkmcnt(0)
	s_barrier
	s_setprio 1
	s_waitcnt lgkmcnt(0)
	v_mfma_f32_16x16x32_bf16 v[62:65], v[150:153], v[182:185], v[62:65]
	v_mfma_f32_16x16x32_bf16 v[62:65], v[154:157], v[186:189], v[62:65]
	v_mfma_f32_16x16x32_bf16 v[50:53], v[150:153], v[190:193], v[50:53]
	v_mfma_f32_16x16x32_bf16 v[50:53], v[154:157], v[210:213], v[50:53]
	v_mfma_f32_16x16x32_bf16 v[34:37], v[150:153], v[214:217], v[34:37]
	v_mfma_f32_16x16x32_bf16 v[34:37], v[154:157], v[230:233], v[34:37]
	v_mfma_f32_16x16x32_bf16 v[18:21], v[150:153], v[234:237], v[18:21]
	v_mfma_f32_16x16x32_bf16 v[18:21], v[154:157], v[238:241], v[18:21]
	v_mfma_f32_16x16x32_bf16 v[58:61], v[158:161], v[182:185], v[58:61]
	v_mfma_f32_16x16x32_bf16 v[58:61], v[162:165], v[186:189], v[58:61]
	v_mfma_f32_16x16x32_bf16 v[42:45], v[158:161], v[190:193], v[42:45]
	v_mfma_f32_16x16x32_bf16 v[42:45], v[162:165], v[210:213], v[42:45]
	v_mfma_f32_16x16x32_bf16 v[26:29], v[158:161], v[214:217], v[26:29]
	v_mfma_f32_16x16x32_bf16 v[26:29], v[162:165], v[230:233], v[26:29]
	v_mfma_f32_16x16x32_bf16 v[10:13], v[158:161], v[234:237], v[10:13]
	v_mfma_f32_16x16x32_bf16 v[10:13], v[162:165], v[238:241], v[10:13]
	s_setprio 0
	s_setprio 1
	v_mfma_f32_16x16x32_bf16 v[54:57], v[166:169], v[182:185], v[54:57]
	v_mfma_f32_16x16x32_bf16 v[54:57], v[170:173], v[186:189], v[54:57]
	v_mfma_f32_16x16x32_bf16 v[38:41], v[166:169], v[190:193], v[38:41]
	v_mfma_f32_16x16x32_bf16 v[38:41], v[170:173], v[210:213], v[38:41]
	v_mfma_f32_16x16x32_bf16 v[22:25], v[166:169], v[214:217], v[22:25]
	v_mfma_f32_16x16x32_bf16 v[22:25], v[170:173], v[230:233], v[22:25]
	v_mfma_f32_16x16x32_bf16 v[6:9], v[166:169], v[234:237], v[6:9]
	v_mfma_f32_16x16x32_bf16 v[6:9], v[170:173], v[238:241], v[6:9]
	v_mfma_f32_16x16x32_bf16 v[46:49], v[174:177], v[182:185], v[46:49]
	v_mfma_f32_16x16x32_bf16 v[46:49], v[178:181], v[186:189], v[46:49]
	v_mfma_f32_16x16x32_bf16 v[30:33], v[174:177], v[190:193], v[30:33]
	v_mfma_f32_16x16x32_bf16 v[30:33], v[178:181], v[210:213], v[30:33]
	v_mfma_f32_16x16x32_bf16 v[14:17], v[174:177], v[214:217], v[14:17]
	v_mfma_f32_16x16x32_bf16 v[14:17], v[178:181], v[230:233], v[14:17]
	v_mfma_f32_16x16x32_bf16 v[2:5], v[174:177], v[234:237], v[2:5]
	v_mfma_f32_16x16x32_bf16 v[2:5], v[178:181], v[238:241], v[2:5]
	s_setprio 0
	s_barrier
	s_add_i32 s29, s29, 2
	s_add_u32 s27, s27, 0x100
	s_addc_u32 s28, s28, 0
	s_add_u32 s90, s90, 0x100
	s_addc_u32 s91, s91, 0
	s_cmp_gt_u32 s29, 29
	s_cbranch_scc0 .LBB0_1207
	s_and_b64 vcc, exec, s[36:37]
	s_cbranch_vccz .LBB0_1210
	s_barrier

.LBB0_1465:
	s_add_u32 s27, s88, 0xfff80080
	s_addc_u32 s28, s89, -1
	s_add_i32 s29, 0, 0x10000
	s_cmp_eq_u32 s26, 28
	s_cselect_b32 s91, s20, s28
	s_cselect_b32 s90, s21, s27
	v_add_u32_e32 v140, s29, v143
	s_cselect_b32 s55, s22, s25
	s_cselect_b32 s54, s23, s24
	s_add_i32 s27, 0, 0x14000
	ds_read_b128 v[146:149], v140
	ds_read_b128 v[150:153], v140 offset:1024
	ds_read_b128 v[154:157], v140 offset:2048
	ds_read_b128 v[158:161], v140 offset:3072
	v_add_u32_e32 v140, s27, v143
	ds_read_b128 v[162:165], v140
	ds_read_b128 v[166:169], v140 offset:1024
	ds_read_b128 v[170:173], v140 offset:2048
	ds_read_b128 v[174:177], v140 offset:3072
	v_lshl_add_u64 v[140:141], s[88:89], 0, v[138:139]
	s_add_i32 m0, s12, 0xc000
	ds_read_b128 v[178:181], v145
	ds_read_b128 v[182:185], v145 offset:1024
	ds_read_b128 v[186:189], v145 offset:2048
	ds_read_b128 v[190:193], v145 offset:3072
	ds_read_b128 v[210:213], v145 offset:4096
	ds_read_b128 v[214:217], v145 offset:5120
	ds_read_b128 v[230:233], v145 offset:6144
	ds_read_b128 v[234:237], v145 offset:7168
	global_load_lds_dwordx4 v[140:141], off
	v_lshl_add_u64 v[140:141], s[88:89], 0, v[136:137]
	s_add_i32 m0, s12, 0xe000
	s_nop 0
	global_load_lds_dwordx4 v[140:141], off
	s_waitcnt vmcnt(8)
	s_waitcnt lgkmcnt(0)
	s_barrier
	s_setprio 1
	s_waitcnt lgkmcnt(0)
	v_mfma_f32_16x16x32_bf16 v[126:129], v[146:149], v[178:181], v[126:129]
	v_mfma_f32_16x16x32_bf16 v[126:129], v[150:153], v[182:185], v[126:129]
	v_mfma_f32_16x16x32_bf16 v[118:121], v[146:149], v[186:189], v[118:121]
	v_mfma_f32_16x16x32_bf16 v[118:121], v[150:153], v[190:193], v[118:121]
	v_mfma_f32_16x16x32_bf16 v[102:105], v[146:149], v[210:213], v[102:105]
	v_mfma_f32_16x16x32_bf16 v[102:105], v[150:153], v[214:217], v[102:105]
	v_mfma_f32_16x16x32_bf16 v[86:89], v[146:149], v[230:233], v[86:89]
	v_mfma_f32_16x16x32_bf16 v[86:89], v[150:153], v[234:237], v[86:89]
	v_mfma_f32_16x16x32_bf16 v[122:125], v[154:157], v[178:181], v[122:125]
	v_mfma_f32_16x16x32_bf16 v[122:125], v[158:161], v[182:185], v[122:125]
	v_mfma_f32_16x16x32_bf16 v[110:113], v[154:157], v[186:189], v[110:113]
	v_mfma_f32_16x16x32_bf16 v[110:113], v[158:161], v[190:193], v[110:113]
	v_mfma_f32_16x16x32_bf16 v[94:97], v[154:157], v[210:213], v[94:97]
	v_mfma_f32_16x16x32_bf16 v[94:97], v[158:161], v[214:217], v[94:97]
	v_mfma_f32_16x16x32_bf16 v[78:81], v[154:157], v[230:233], v[78:81]
	v_mfma_f32_16x16x32_bf16 v[78:81], v[158:161], v[234:237], v[78:81]
	s_setprio 0
	s_setprio 1
	v_mfma_f32_16x16x32_bf16 v[114:117], v[162:165], v[178:181], v[114:117]
	v_mfma_f32_16x16x32_bf16 v[114:117], v[166:169], v[182:185], v[114:117]
	v_mfma_f32_16x16x32_bf16 v[98:101], v[162:165], v[186:189], v[98:101]
	v_mfma_f32_16x16x32_bf16 v[98:101], v[166:169], v[190:193], v[98:101]
	v_mfma_f32_16x16x32_bf16 v[82:85], v[162:165], v[210:213], v[82:85]
	v_mfma_f32_16x16x32_bf16 v[82:85], v[166:169], v[214:217], v[82:85]
	v_mfma_f32_16x16x32_bf16 v[70:73], v[162:165], v[230:233], v[70:73]
	v_mfma_f32_16x16x32_bf16 v[70:73], v[166:169], v[234:237], v[70:73]
	v_mfma_f32_16x16x32_bf16 v[106:109], v[170:173], v[178:181], v[106:109]
	v_mfma_f32_16x16x32_bf16 v[106:109], v[174:177], v[182:185], v[106:109]
	v_mfma_f32_16x16x32_bf16 v[90:93], v[170:173], v[186:189], v[90:93]
	v_mfma_f32_16x16x32_bf16 v[90:93], v[174:177], v[190:193], v[90:93]
	v_mfma_f32_16x16x32_bf16 v[74:77], v[170:173], v[210:213], v[74:77]
	v_mfma_f32_16x16x32_bf16 v[74:77], v[174:177], v[214:217], v[74:77]
	v_mfma_f32_16x16x32_bf16 v[66:69], v[170:173], v[230:233], v[66:69]
	v_mfma_f32_16x16x32_bf16 v[66:69], v[174:177], v[234:237], v[66:69]
	s_setprio 0
	s_barrier
	s_add_i32 s28, s29, s11
	v_lshl_add_u64 v[140:141], s[54:55], 0, v[194:195]
	s_mov_b32 m0, s28
	ds_read_b128 v[178:181], v145 offset:16384
	ds_read_b128 v[182:185], v145 offset:17408
	ds_read_b128 v[186:189], v145 offset:18432
	ds_read_b128 v[190:193], v145 offset:19456
	ds_read_b128 v[210:213], v145 offset:20480
	ds_read_b128 v[214:217], v145 offset:21504
	ds_read_b128 v[230:233], v145 offset:22528
	ds_read_b128 v[234:237], v145 offset:23552
	global_load_lds_dwordx4 v[140:141], off
	s_add_i32 m0, s28, 0x2000
	s_add_u32 s28, s54, 0x80000
	v_lshl_add_u64 v[218:219], s[54:55], 0, v[134:135]
	s_addc_u32 s29, s55, 0
	s_add_i32 s27, s27, s11
	global_load_lds_dwordx4 v[218:219], off
	v_lshl_add_u64 v[238:239], s[28:29], 0, v[194:195]
	s_mov_b32 m0, s27
	v_lshl_add_u64 v[240:241], s[90:91], 0, v[132:133]
	global_load_lds_dwordx4 v[238:239], off
	v_lshl_add_u64 v[238:239], s[28:29], 0, v[134:135]
	s_add_i32 m0, s27, 0x2000
	s_nop 0
	global_load_lds_dwordx4 v[238:239], off
	v_lshl_add_u64 v[238:239], s[90:91], 0, v[130:131]
	s_mov_b32 m0, s12
	s_nop 0
	global_load_lds_dwordx4 v[238:239], off
	s_mov_b32 m0, s13
	s_nop 0
	global_load_lds_dwordx4 v[240:241], off
	s_waitcnt vmcnt(8)
	s_waitcnt lgkmcnt(0)
	s_barrier
	s_setprio 1
	s_waitcnt lgkmcnt(0)
	v_mfma_f32_16x16x32_bf16 v[62:65], v[146:149], v[178:181], v[62:65]
	v_mfma_f32_16x16x32_bf16 v[62:65], v[150:153], v[182:185], v[62:65]
	v_mfma_f32_16x16x32_bf16 v[54:57], v[146:149], v[186:189], v[54:57]
	v_mfma_f32_16x16x32_bf16 v[54:57], v[150:153], v[190:193], v[54:57]
	v_mfma_f32_16x16x32_bf16 v[38:41], v[146:149], v[210:213], v[38:41]
	v_mfma_f32_16x16x32_bf16 v[38:41], v[150:153], v[214:217], v[38:41]
	v_mfma_f32_16x16x32_bf16 v[22:25], v[146:149], v[230:233], v[22:25]
	v_mfma_f32_16x16x32_bf16 v[22:25], v[150:153], v[234:237], v[22:25]
	v_mfma_f32_16x16x32_bf16 v[58:61], v[154:157], v[178:181], v[58:61]
	v_mfma_f32_16x16x32_bf16 v[58:61], v[158:161], v[182:185], v[58:61]
	v_mfma_f32_16x16x32_bf16 v[46:49], v[154:157], v[186:189], v[46:49]
	v_mfma_f32_16x16x32_bf16 v[46:49], v[158:161], v[190:193], v[46:49]
	v_mfma_f32_16x16x32_bf16 v[30:33], v[154:157], v[210:213], v[30:33]
	v_mfma_f32_16x16x32_bf16 v[30:33], v[158:161], v[214:217], v[30:33]
	v_mfma_f32_16x16x32_bf16 v[14:17], v[154:157], v[230:233], v[14:17]
	v_mfma_f32_16x16x32_bf16 v[14:17], v[158:161], v[234:237], v[14:17]
	s_setprio 0
	s_setprio 1
	v_mfma_f32_16x16x32_bf16 v[50:53], v[162:165], v[178:181], v[50:53]
	v_mfma_f32_16x16x32_bf16 v[50:53], v[166:169], v[182:185], v[50:53]
	v_mfma_f32_16x16x32_bf16 v[34:37], v[162:165], v[186:189], v[34:37]
	v_mfma_f32_16x16x32_bf16 v[34:37], v[166:169], v[190:193], v[34:37]
	v_mfma_f32_16x16x32_bf16 v[18:21], v[162:165], v[210:213], v[18:21]
	v_mfma_f32_16x16x32_bf16 v[18:21], v[166:169], v[214:217], v[18:21]
	v_mfma_f32_16x16x32_bf16 v[6:9], v[162:165], v[230:233], v[6:9]
	v_mfma_f32_16x16x32_bf16 v[6:9], v[166:169], v[234:237], v[6:9]
	v_mfma_f32_16x16x32_bf16 v[42:45], v[170:173], v[178:181], v[42:45]
	v_mfma_f32_16x16x32_bf16 v[42:45], v[174:177], v[182:185], v[42:45]
	v_mfma_f32_16x16x32_bf16 v[26:29], v[170:173], v[186:189], v[26:29]
	v_mfma_f32_16x16x32_bf16 v[26:29], v[174:177], v[190:193], v[26:29]
	v_mfma_f32_16x16x32_bf16 v[10:13], v[170:173], v[210:213], v[10:13]
	v_mfma_f32_16x16x32_bf16 v[10:13], v[174:177], v[214:217], v[10:13]
	v_mfma_f32_16x16x32_bf16 v[2:5], v[170:173], v[230:233], v[2:5]
	v_mfma_f32_16x16x32_bf16 v[2:5], v[174:177], v[234:237], v[2:5]
	s_setprio 0
	s_barrier
	s_add_i32 s27, 0, 0x18000
	s_add_i32 s30, 0, 0x1c000
	v_add_u32_e32 v158, s27, v143
	v_add_u32_e32 v174, s30, v143
	ds_read_b128 v[146:149], v158
	ds_read_b128 v[150:153], v158 offset:1024
	ds_read_b128 v[154:157], v158 offset:2048
	ds_read_b128 v[158:161], v158 offset:3072
	ds_read_b128 v[162:165], v174
	ds_read_b128 v[166:169], v174 offset:1024
	ds_read_b128 v[170:173], v174 offset:2048
	ds_read_b128 v[174:177], v174 offset:3072
	s_add_u32 s28, s90, 0x80000
	s_addc_u32 s29, s91, 0
	s_mov_b32 m0, s14
	v_lshl_add_u64 v[242:243], s[28:29], 0, v[130:131]
	ds_read_b128 v[178:181], v145 offset:32768
	ds_read_b128 v[182:185], v145 offset:33792
	ds_read_b128 v[186:189], v145 offset:34816
	ds_read_b128 v[190:193], v145 offset:35840
	ds_read_b128 v[210:213], v145 offset:36864
	ds_read_b128 v[214:217], v145 offset:37888
	ds_read_b128 v[230:233], v145 offset:38912
	ds_read_b128 v[234:237], v145 offset:39936
	global_load_lds_dwordx4 v[242:243], off
	v_lshl_add_u64 v[242:243], s[28:29], 0, v[132:133]
	s_mov_b32 m0, s15
	s_nop 0
	global_load_lds_dwordx4 v[242:243], off
	s_waitcnt vmcnt(8)
	s_waitcnt lgkmcnt(0)
	s_barrier
	s_setprio 1
	s_waitcnt lgkmcnt(0)
	v_mfma_f32_16x16x32_bf16 v[126:129], v[146:149], v[178:181], v[126:129]
	v_mfma_f32_16x16x32_bf16 v[126:129], v[150:153], v[182:185], v[126:129]
	v_mfma_f32_16x16x32_bf16 v[118:121], v[146:149], v[186:189], v[118:121]
	v_mfma_f32_16x16x32_bf16 v[118:121], v[150:153], v[190:193], v[118:121]
	v_mfma_f32_16x16x32_bf16 v[102:105], v[146:149], v[210:213], v[102:105]
	v_mfma_f32_16x16x32_bf16 v[102:105], v[150:153], v[214:217], v[102:105]
	v_mfma_f32_16x16x32_bf16 v[86:89], v[146:149], v[230:233], v[86:89]
	v_mfma_f32_16x16x32_bf16 v[86:89], v[150:153], v[234:237], v[86:89]
	v_mfma_f32_16x16x32_bf16 v[122:125], v[154:157], v[178:181], v[122:125]
	v_mfma_f32_16x16x32_bf16 v[122:125], v[158:161], v[182:185], v[122:125]
	v_mfma_f32_16x16x32_bf16 v[110:113], v[154:157], v[186:189], v[110:113]
	v_mfma_f32_16x16x32_bf16 v[110:113], v[158:161], v[190:193], v[110:113]
	v_mfma_f32_16x16x32_bf16 v[94:97], v[154:157], v[210:213], v[94:97]
	v_mfma_f32_16x16x32_bf16 v[94:97], v[158:161], v[214:217], v[94:97]
	v_mfma_f32_16x16x32_bf16 v[78:81], v[154:157], v[230:233], v[78:81]
	v_mfma_f32_16x16x32_bf16 v[78:81], v[158:161], v[234:237], v[78:81]
	s_setprio 0
	s_setprio 1
	v_mfma_f32_16x16x32_bf16 v[114:117], v[162:165], v[178:181], v[114:117]
	v_mfma_f32_16x16x32_bf16 v[114:117], v[166:169], v[182:185], v[114:117]
	v_mfma_f32_16x16x32_bf16 v[98:101], v[162:165], v[186:189], v[98:101]
	v_mfma_f32_16x16x32_bf16 v[98:101], v[166:169], v[190:193], v[98:101]
	v_mfma_f32_16x16x32_bf16 v[82:85], v[162:165], v[210:213], v[82:85]
	v_mfma_f32_16x16x32_bf16 v[82:85], v[166:169], v[214:217], v[82:85]
	v_mfma_f32_16x16x32_bf16 v[70:73], v[162:165], v[230:233], v[70:73]
	v_mfma_f32_16x16x32_bf16 v[70:73], v[166:169], v[234:237], v[70:73]
	v_mfma_f32_16x16x32_bf16 v[106:109], v[170:173], v[178:181], v[106:109]
	v_mfma_f32_16x16x32_bf16 v[106:109], v[174:177], v[182:185], v[106:109]
	v_mfma_f32_16x16x32_bf16 v[90:93], v[170:173], v[186:189], v[90:93]
	v_mfma_f32_16x16x32_bf16 v[90:93], v[174:177], v[190:193], v[90:93]
	v_mfma_f32_16x16x32_bf16 v[74:77], v[170:173], v[210:213], v[74:77]
	v_mfma_f32_16x16x32_bf16 v[74:77], v[174:177], v[214:217], v[74:77]
	v_mfma_f32_16x16x32_bf16 v[66:69], v[170:173], v[230:233], v[66:69]
	v_mfma_f32_16x16x32_bf16 v[66:69], v[174:177], v[234:237], v[66:69]
	s_setprio 0
	s_barrier
	s_add_i32 s27, s27, s11
	v_lshl_add_u64 v[140:141], v[140:141], 0, s[56:57]
	s_mov_b32 m0, s27
	ds_read_b128 v[178:181], v145 offset:49152
	ds_read_b128 v[182:185], v145 offset:50176
	ds_read_b128 v[186:189], v145 offset:51200
	ds_read_b128 v[190:193], v145 offset:52224
	ds_read_b128 v[210:213], v145 offset:53248
	ds_read_b128 v[214:217], v145 offset:54272
	ds_read_b128 v[230:233], v145 offset:55296
	ds_read_b128 v[234:237], v145 offset:56320
	global_load_lds_dwordx4 v[140:141], off
	s_add_i32 m0, s27, 0x2000
	s_add_u32 s28, s54, 0x80080
	v_lshl_add_u64 v[140:141], v[218:219], 0, s[56:57]
	s_addc_u32 s29, s55, 0
	s_add_i32 s27, s30, s11
	global_load_lds_dwordx4 v[140:141], off
	v_lshl_add_u64 v[140:141], s[28:29], 0, v[194:195]
	s_mov_b32 m0, s27
	s_nop 0
	global_load_lds_dwordx4 v[140:141], off
	v_lshl_add_u64 v[140:141], s[28:29], 0, v[134:135]
	s_add_i32 m0, s27, 0x2000
	s_nop 0
	global_load_lds_dwordx4 v[140:141], off
	v_lshl_add_u64 v[140:141], v[238:239], 0, s[56:57]
	s_mov_b32 m0, s16
	s_nop 0
	global_load_lds_dwordx4 v[140:141], off
	v_lshl_add_u64 v[140:141], v[240:241], 0, s[56:57]
	s_mov_b32 m0, s17
	s_nop 0
	global_load_lds_dwordx4 v[140:141], off
	s_waitcnt vmcnt(8)
	s_waitcnt lgkmcnt(0)
	s_barrier
	s_setprio 1
	s_waitcnt lgkmcnt(0)
	v_mfma_f32_16x16x32_bf16 v[62:65], v[146:149], v[178:181], v[62:65]
	v_mfma_f32_16x16x32_bf16 v[62:65], v[150:153], v[182:185], v[62:65]
	v_mfma_f32_16x16x32_bf16 v[54:57], v[146:149], v[186:189], v[54:57]
	v_mfma_f32_16x16x32_bf16 v[54:57], v[150:153], v[190:193], v[54:57]
	v_mfma_f32_16x16x32_bf16 v[38:41], v[146:149], v[210:213], v[38:41]
	v_mfma_f32_16x16x32_bf16 v[38:41], v[150:153], v[214:217], v[38:41]
	v_mfma_f32_16x16x32_bf16 v[22:25], v[146:149], v[230:233], v[22:25]
	v_mfma_f32_16x16x32_bf16 v[22:25], v[150:153], v[234:237], v[22:25]
	v_mfma_f32_16x16x32_bf16 v[58:61], v[154:157], v[178:181], v[58:61]
	v_mfma_f32_16x16x32_bf16 v[58:61], v[158:161], v[182:185], v[58:61]
	v_mfma_f32_16x16x32_bf16 v[46:49], v[154:157], v[186:189], v[46:49]
	v_mfma_f32_16x16x32_bf16 v[46:49], v[158:161], v[190:193], v[46:49]
	v_mfma_f32_16x16x32_bf16 v[30:33], v[154:157], v[210:213], v[30:33]
	v_mfma_f32_16x16x32_bf16 v[30:33], v[158:161], v[214:217], v[30:33]
	v_mfma_f32_16x16x32_bf16 v[14:17], v[154:157], v[230:233], v[14:17]
	v_mfma_f32_16x16x32_bf16 v[14:17], v[158:161], v[234:237], v[14:17]
	s_setprio 0
	s_setprio 1
	v_mfma_f32_16x16x32_bf16 v[50:53], v[162:165], v[178:181], v[50:53]
	v_mfma_f32_16x16x32_bf16 v[50:53], v[166:169], v[182:185], v[50:53]
	v_mfma_f32_16x16x32_bf16 v[34:37], v[162:165], v[186:189], v[34:37]
	v_mfma_f32_16x16x32_bf16 v[34:37], v[166:169], v[190:193], v[34:37]
	v_mfma_f32_16x16x32_bf16 v[18:21], v[162:165], v[210:213], v[18:21]
	v_mfma_f32_16x16x32_bf16 v[18:21], v[166:169], v[214:217], v[18:21]
	v_mfma_f32_16x16x32_bf16 v[6:9], v[162:165], v[230:233], v[6:9]
	v_mfma_f32_16x16x32_bf16 v[6:9], v[166:169], v[234:237], v[6:9]
	v_mfma_f32_16x16x32_bf16 v[42:45], v[170:173], v[178:181], v[42:45]
	v_mfma_f32_16x16x32_bf16 v[42:45], v[174:177], v[182:185], v[42:45]
	v_mfma_f32_16x16x32_bf16 v[26:29], v[170:173], v[186:189], v[26:29]
	v_mfma_f32_16x16x32_bf16 v[26:29], v[174:177], v[190:193], v[26:29]
	v_mfma_f32_16x16x32_bf16 v[10:13], v[170:173], v[210:213], v[10:13]
	v_mfma_f32_16x16x32_bf16 v[10:13], v[174:177], v[214:217], v[10:13]
	v_mfma_f32_16x16x32_bf16 v[2:5], v[170:173], v[230:233], v[2:5]
	v_mfma_f32_16x16x32_bf16 v[2:5], v[174:177], v[234:237], v[2:5]
	s_setprio 0
	s_barrier
	s_add_i32 s26, s26, 2
	s_add_u32 s24, s24, 0x100
	s_addc_u32 s25, s25, 0
	s_add_u32 s88, s88, 0x100
	s_addc_u32 s89, s89, 0
	s_cmp_gt_u32 s26, 29
	s_cbranch_scc0 .LBB0_1465
	s_and_b64 vcc, exec, s[44:45]
	s_cbranch_vccz .LBB0_1468
	s_barrier

.LBB0_1609:
	s_add_u32 s29, s90, 0xfff80080
	s_addc_u32 s30, s91, -1
	s_add_i32 s31, 0, 0x10000
	s_cmp_eq_u32 s28, 28
	s_cselect_b32 vcc_hi, s22, s30
	s_cselect_b32 vcc_lo, s23, s29
	v_add_u32_e32 v140, s31, v143
	s_cselect_b32 s55, s24, s27
	s_cselect_b32 s54, s25, s26
	s_add_i32 s29, 0, 0x14000
	ds_read_b128 v[146:149], v140
	ds_read_b128 v[150:153], v140 offset:1024
	ds_read_b128 v[154:157], v140 offset:2048
	ds_read_b128 v[158:161], v140 offset:3072
	v_add_u32_e32 v140, s29, v143
	ds_read_b128 v[162:165], v140
	ds_read_b128 v[166:169], v140 offset:1024
	ds_read_b128 v[170:173], v140 offset:2048
	ds_read_b128 v[174:177], v140 offset:3072
	v_lshl_add_u64 v[140:141], s[90:91], 0, v[138:139]
	s_add_i32 m0, s14, 0xc000
	ds_read_b128 v[178:181], v145
	ds_read_b128 v[182:185], v145 offset:1024
	ds_read_b128 v[186:189], v145 offset:2048
	ds_read_b128 v[190:193], v145 offset:3072
	ds_read_b128 v[210:213], v145 offset:4096
	ds_read_b128 v[214:217], v145 offset:5120
	ds_read_b128 v[230:233], v145 offset:6144
	ds_read_b128 v[234:237], v145 offset:7168
	global_load_lds_dwordx4 v[140:141], off
	v_lshl_add_u64 v[140:141], s[90:91], 0, v[136:137]
	s_add_i32 m0, s14, 0xe000
	s_nop 0
	global_load_lds_dwordx4 v[140:141], off
	s_waitcnt vmcnt(8)
	s_waitcnt lgkmcnt(0)
	s_barrier
	s_setprio 1
	s_waitcnt lgkmcnt(0)
	v_mfma_f32_16x16x32_bf16 v[126:129], v[146:149], v[178:181], v[126:129]
	v_mfma_f32_16x16x32_bf16 v[126:129], v[150:153], v[182:185], v[126:129]
	v_mfma_f32_16x16x32_bf16 v[110:113], v[146:149], v[186:189], v[110:113]
	v_mfma_f32_16x16x32_bf16 v[110:113], v[150:153], v[190:193], v[110:113]
	v_mfma_f32_16x16x32_bf16 v[94:97], v[146:149], v[210:213], v[94:97]
	v_mfma_f32_16x16x32_bf16 v[94:97], v[150:153], v[214:217], v[94:97]
	v_mfma_f32_16x16x32_bf16 v[78:81], v[146:149], v[230:233], v[78:81]
	v_mfma_f32_16x16x32_bf16 v[78:81], v[150:153], v[234:237], v[78:81]
	v_mfma_f32_16x16x32_bf16 v[122:125], v[154:157], v[178:181], v[122:125]
	v_mfma_f32_16x16x32_bf16 v[122:125], v[158:161], v[182:185], v[122:125]
	v_mfma_f32_16x16x32_bf16 v[106:109], v[154:157], v[186:189], v[106:109]
	v_mfma_f32_16x16x32_bf16 v[106:109], v[158:161], v[190:193], v[106:109]
	v_mfma_f32_16x16x32_bf16 v[90:93], v[154:157], v[210:213], v[90:93]
	v_mfma_f32_16x16x32_bf16 v[90:93], v[158:161], v[214:217], v[90:93]
	v_mfma_f32_16x16x32_bf16 v[74:77], v[154:157], v[230:233], v[74:77]
	v_mfma_f32_16x16x32_bf16 v[74:77], v[158:161], v[234:237], v[74:77]
	s_setprio 0
	s_setprio 1
	v_mfma_f32_16x16x32_bf16 v[118:121], v[162:165], v[178:181], v[118:121]
	v_mfma_f32_16x16x32_bf16 v[118:121], v[166:169], v[182:185], v[118:121]
	v_mfma_f32_16x16x32_bf16 v[102:105], v[162:165], v[186:189], v[102:105]
	v_mfma_f32_16x16x32_bf16 v[102:105], v[166:169], v[190:193], v[102:105]
	v_mfma_f32_16x16x32_bf16 v[86:89], v[162:165], v[210:213], v[86:89]
	v_mfma_f32_16x16x32_bf16 v[86:89], v[166:169], v[214:217], v[86:89]
	v_mfma_f32_16x16x32_bf16 v[70:73], v[162:165], v[230:233], v[70:73]
	v_mfma_f32_16x16x32_bf16 v[70:73], v[166:169], v[234:237], v[70:73]
	v_mfma_f32_16x16x32_bf16 v[114:117], v[170:173], v[178:181], v[114:117]
	v_mfma_f32_16x16x32_bf16 v[114:117], v[174:177], v[182:185], v[114:117]
	v_mfma_f32_16x16x32_bf16 v[98:101], v[170:173], v[186:189], v[98:101]
	v_mfma_f32_16x16x32_bf16 v[98:101], v[174:177], v[190:193], v[98:101]
	v_mfma_f32_16x16x32_bf16 v[82:85], v[170:173], v[210:213], v[82:85]
	v_mfma_f32_16x16x32_bf16 v[82:85], v[174:177], v[214:217], v[82:85]
	v_mfma_f32_16x16x32_bf16 v[66:69], v[170:173], v[230:233], v[66:69]
	v_mfma_f32_16x16x32_bf16 v[66:69], v[174:177], v[234:237], v[66:69]
	s_setprio 0
	s_barrier
	s_add_i32 s30, s31, s13
	v_lshl_add_u64 v[140:141], s[54:55], 0, v[194:195]
	s_mov_b32 m0, s30
	ds_read_b128 v[178:181], v145 offset:16384
	ds_read_b128 v[182:185], v145 offset:17408
	ds_read_b128 v[186:189], v145 offset:18432
	ds_read_b128 v[190:193], v145 offset:19456
	ds_read_b128 v[210:213], v145 offset:20480
	ds_read_b128 v[214:217], v145 offset:21504
	ds_read_b128 v[230:233], v145 offset:22528
	ds_read_b128 v[234:237], v145 offset:23552
	global_load_lds_dwordx4 v[140:141], off
	s_add_i32 m0, s30, 0x2000
	s_add_u32 s30, s54, 0x80000
	v_lshl_add_u64 v[218:219], s[54:55], 0, v[134:135]
	s_addc_u32 s31, s55, 0
	s_add_i32 s29, s29, s13
	global_load_lds_dwordx4 v[218:219], off
	v_lshl_add_u64 v[238:239], s[30:31], 0, v[194:195]
	s_mov_b32 m0, s29
	v_lshl_add_u64 v[240:241], vcc, 0, v[132:133]
	global_load_lds_dwordx4 v[238:239], off
	v_lshl_add_u64 v[238:239], s[30:31], 0, v[134:135]
	s_add_i32 m0, s29, 0x2000
	s_nop 0
	global_load_lds_dwordx4 v[238:239], off
	v_lshl_add_u64 v[238:239], vcc, 0, v[130:131]
	s_mov_b32 m0, s14
	s_nop 0
	global_load_lds_dwordx4 v[238:239], off
	s_mov_b32 m0, s15
	s_nop 0
	global_load_lds_dwordx4 v[240:241], off
	s_waitcnt vmcnt(8)
	s_waitcnt lgkmcnt(0)
	s_barrier
	s_setprio 1
	s_waitcnt lgkmcnt(0)
	v_mfma_f32_16x16x32_bf16 v[62:65], v[146:149], v[178:181], v[62:65]
	v_mfma_f32_16x16x32_bf16 v[62:65], v[150:153], v[182:185], v[62:65]
	v_mfma_f32_16x16x32_bf16 v[46:49], v[146:149], v[186:189], v[46:49]
	v_mfma_f32_16x16x32_bf16 v[46:49], v[150:153], v[190:193], v[46:49]
	v_mfma_f32_16x16x32_bf16 v[30:33], v[146:149], v[210:213], v[30:33]
	v_mfma_f32_16x16x32_bf16 v[30:33], v[150:153], v[214:217], v[30:33]
	v_mfma_f32_16x16x32_bf16 v[14:17], v[146:149], v[230:233], v[14:17]
	v_mfma_f32_16x16x32_bf16 v[14:17], v[150:153], v[234:237], v[14:17]
	v_mfma_f32_16x16x32_bf16 v[58:61], v[154:157], v[178:181], v[58:61]
	v_mfma_f32_16x16x32_bf16 v[58:61], v[158:161], v[182:185], v[58:61]
	v_mfma_f32_16x16x32_bf16 v[42:45], v[154:157], v[186:189], v[42:45]
	v_mfma_f32_16x16x32_bf16 v[42:45], v[158:161], v[190:193], v[42:45]
	v_mfma_f32_16x16x32_bf16 v[26:29], v[154:157], v[210:213], v[26:29]
	v_mfma_f32_16x16x32_bf16 v[26:29], v[158:161], v[214:217], v[26:29]
	v_mfma_f32_16x16x32_bf16 v[10:13], v[154:157], v[230:233], v[10:13]
	v_mfma_f32_16x16x32_bf16 v[10:13], v[158:161], v[234:237], v[10:13]
	s_setprio 0
	s_setprio 1
	v_mfma_f32_16x16x32_bf16 v[54:57], v[162:165], v[178:181], v[54:57]
	v_mfma_f32_16x16x32_bf16 v[54:57], v[166:169], v[182:185], v[54:57]
	v_mfma_f32_16x16x32_bf16 v[38:41], v[162:165], v[186:189], v[38:41]
	v_mfma_f32_16x16x32_bf16 v[38:41], v[166:169], v[190:193], v[38:41]
	v_mfma_f32_16x16x32_bf16 v[22:25], v[162:165], v[210:213], v[22:25]
	v_mfma_f32_16x16x32_bf16 v[22:25], v[166:169], v[214:217], v[22:25]
	v_mfma_f32_16x16x32_bf16 v[6:9], v[162:165], v[230:233], v[6:9]
	v_mfma_f32_16x16x32_bf16 v[6:9], v[166:169], v[234:237], v[6:9]
	v_mfma_f32_16x16x32_bf16 v[50:53], v[170:173], v[178:181], v[50:53]
	v_mfma_f32_16x16x32_bf16 v[50:53], v[174:177], v[182:185], v[50:53]
	v_mfma_f32_16x16x32_bf16 v[34:37], v[170:173], v[186:189], v[34:37]
	v_mfma_f32_16x16x32_bf16 v[34:37], v[174:177], v[190:193], v[34:37]
	v_mfma_f32_16x16x32_bf16 v[18:21], v[170:173], v[210:213], v[18:21]
	v_mfma_f32_16x16x32_bf16 v[18:21], v[174:177], v[214:217], v[18:21]
	v_mfma_f32_16x16x32_bf16 v[2:5], v[170:173], v[230:233], v[2:5]
	v_mfma_f32_16x16x32_bf16 v[2:5], v[174:177], v[234:237], v[2:5]
	s_setprio 0
	s_barrier
	s_add_i32 s29, 0, 0x18000
	s_add_i32 s45, 0, 0x1c000
	v_add_u32_e32 v158, s29, v143
	v_add_u32_e32 v174, s45, v143
	ds_read_b128 v[146:149], v158
	ds_read_b128 v[150:153], v158 offset:1024
	ds_read_b128 v[154:157], v158 offset:2048
	ds_read_b128 v[158:161], v158 offset:3072
	ds_read_b128 v[162:165], v174
	ds_read_b128 v[166:169], v174 offset:1024
	ds_read_b128 v[170:173], v174 offset:2048
	ds_read_b128 v[174:177], v174 offset:3072
	s_add_u32 s30, vcc_lo, 0x80000
	s_addc_u32 s31, vcc_hi, 0
	s_mov_b32 m0, s16
	v_lshl_add_u64 v[242:243], s[30:31], 0, v[130:131]
	ds_read_b128 v[178:181], v145 offset:32768
	ds_read_b128 v[182:185], v145 offset:33792
	ds_read_b128 v[186:189], v145 offset:34816
	ds_read_b128 v[190:193], v145 offset:35840
	ds_read_b128 v[210:213], v145 offset:36864
	ds_read_b128 v[214:217], v145 offset:37888
	ds_read_b128 v[230:233], v145 offset:38912
	ds_read_b128 v[234:237], v145 offset:39936
	global_load_lds_dwordx4 v[242:243], off
	v_lshl_add_u64 v[242:243], s[30:31], 0, v[132:133]
	s_mov_b32 m0, s17
	s_nop 0
	global_load_lds_dwordx4 v[242:243], off
	s_waitcnt vmcnt(8)
	s_waitcnt lgkmcnt(0)
	s_barrier
	s_setprio 1
	s_waitcnt lgkmcnt(0)
	v_mfma_f32_16x16x32_bf16 v[126:129], v[146:149], v[178:181], v[126:129]
	v_mfma_f32_16x16x32_bf16 v[126:129], v[150:153], v[182:185], v[126:129]
	v_mfma_f32_16x16x32_bf16 v[110:113], v[146:149], v[186:189], v[110:113]
	v_mfma_f32_16x16x32_bf16 v[110:113], v[150:153], v[190:193], v[110:113]
	v_mfma_f32_16x16x32_bf16 v[94:97], v[146:149], v[210:213], v[94:97]
	v_mfma_f32_16x16x32_bf16 v[94:97], v[150:153], v[214:217], v[94:97]
	v_mfma_f32_16x16x32_bf16 v[78:81], v[146:149], v[230:233], v[78:81]
	v_mfma_f32_16x16x32_bf16 v[78:81], v[150:153], v[234:237], v[78:81]
	v_mfma_f32_16x16x32_bf16 v[122:125], v[154:157], v[178:181], v[122:125]
	v_mfma_f32_16x16x32_bf16 v[122:125], v[158:161], v[182:185], v[122:125]
	v_mfma_f32_16x16x32_bf16 v[106:109], v[154:157], v[186:189], v[106:109]
	v_mfma_f32_16x16x32_bf16 v[106:109], v[158:161], v[190:193], v[106:109]
	v_mfma_f32_16x16x32_bf16 v[90:93], v[154:157], v[210:213], v[90:93]
	v_mfma_f32_16x16x32_bf16 v[90:93], v[158:161], v[214:217], v[90:93]
	v_mfma_f32_16x16x32_bf16 v[74:77], v[154:157], v[230:233], v[74:77]
	v_mfma_f32_16x16x32_bf16 v[74:77], v[158:161], v[234:237], v[74:77]
	s_setprio 0
	s_setprio 1
	v_mfma_f32_16x16x32_bf16 v[118:121], v[162:165], v[178:181], v[118:121]
	v_mfma_f32_16x16x32_bf16 v[118:121], v[166:169], v[182:185], v[118:121]
	v_mfma_f32_16x16x32_bf16 v[102:105], v[162:165], v[186:189], v[102:105]
	v_mfma_f32_16x16x32_bf16 v[102:105], v[166:169], v[190:193], v[102:105]
	v_mfma_f32_16x16x32_bf16 v[86:89], v[162:165], v[210:213], v[86:89]
	v_mfma_f32_16x16x32_bf16 v[86:89], v[166:169], v[214:217], v[86:89]
	v_mfma_f32_16x16x32_bf16 v[70:73], v[162:165], v[230:233], v[70:73]
	v_mfma_f32_16x16x32_bf16 v[70:73], v[166:169], v[234:237], v[70:73]
	v_mfma_f32_16x16x32_bf16 v[114:117], v[170:173], v[178:181], v[114:117]
	v_mfma_f32_16x16x32_bf16 v[114:117], v[174:177], v[182:185], v[114:117]
	v_mfma_f32_16x16x32_bf16 v[98:101], v[170:173], v[186:189], v[98:101]
	v_mfma_f32_16x16x32_bf16 v[98:101], v[174:177], v[190:193], v[98:101]
	v_mfma_f32_16x16x32_bf16 v[82:85], v[170:173], v[210:213], v[82:85]
	v_mfma_f32_16x16x32_bf16 v[82:85], v[174:177], v[214:217], v[82:85]
	v_mfma_f32_16x16x32_bf16 v[66:69], v[170:173], v[230:233], v[66:69]
	v_mfma_f32_16x16x32_bf16 v[66:69], v[174:177], v[234:237], v[66:69]
	s_setprio 0
	s_barrier
	s_add_i32 s29, s29, s13
	v_lshl_add_u64 v[140:141], v[140:141], 0, s[56:57]
	s_mov_b32 m0, s29
	ds_read_b128 v[178:181], v145 offset:49152
	ds_read_b128 v[182:185], v145 offset:50176
	ds_read_b128 v[186:189], v145 offset:51200
	ds_read_b128 v[190:193], v145 offset:52224
	ds_read_b128 v[210:213], v145 offset:53248
	ds_read_b128 v[214:217], v145 offset:54272
	ds_read_b128 v[230:233], v145 offset:55296
	ds_read_b128 v[234:237], v145 offset:56320
	global_load_lds_dwordx4 v[140:141], off
	s_add_i32 m0, s29, 0x2000
	s_add_u32 s30, s54, 0x80080
	v_lshl_add_u64 v[140:141], v[218:219], 0, s[56:57]
	s_addc_u32 s31, s55, 0
	s_add_i32 s29, s45, s13
	global_load_lds_dwordx4 v[140:141], off
	v_lshl_add_u64 v[140:141], s[30:31], 0, v[194:195]
	s_mov_b32 m0, s29
	s_nop 0
	global_load_lds_dwordx4 v[140:141], off
	v_lshl_add_u64 v[140:141], s[30:31], 0, v[134:135]
	s_add_i32 m0, s29, 0x2000
	s_nop 0
	global_load_lds_dwordx4 v[140:141], off
	v_lshl_add_u64 v[140:141], v[238:239], 0, s[56:57]
	s_mov_b32 m0, s18
	s_nop 0
	global_load_lds_dwordx4 v[140:141], off
	v_lshl_add_u64 v[140:141], v[240:241], 0, s[56:57]
	s_mov_b32 m0, s19
	s_nop 0
	global_load_lds_dwordx4 v[140:141], off
	s_waitcnt vmcnt(8)
	s_waitcnt lgkmcnt(0)
	s_barrier
	s_setprio 1
	s_waitcnt lgkmcnt(0)
	v_mfma_f32_16x16x32_bf16 v[62:65], v[146:149], v[178:181], v[62:65]
	v_mfma_f32_16x16x32_bf16 v[62:65], v[150:153], v[182:185], v[62:65]
	v_mfma_f32_16x16x32_bf16 v[46:49], v[146:149], v[186:189], v[46:49]
	v_mfma_f32_16x16x32_bf16 v[46:49], v[150:153], v[190:193], v[46:49]
	v_mfma_f32_16x16x32_bf16 v[30:33], v[146:149], v[210:213], v[30:33]
	v_mfma_f32_16x16x32_bf16 v[30:33], v[150:153], v[214:217], v[30:33]
	v_mfma_f32_16x16x32_bf16 v[14:17], v[146:149], v[230:233], v[14:17]
	v_mfma_f32_16x16x32_bf16 v[14:17], v[150:153], v[234:237], v[14:17]
	v_mfma_f32_16x16x32_bf16 v[58:61], v[154:157], v[178:181], v[58:61]
	v_mfma_f32_16x16x32_bf16 v[58:61], v[158:161], v[182:185], v[58:61]
	v_mfma_f32_16x16x32_bf16 v[42:45], v[154:157], v[186:189], v[42:45]
	v_mfma_f32_16x16x32_bf16 v[42:45], v[158:161], v[190:193], v[42:45]
	v_mfma_f32_16x16x32_bf16 v[26:29], v[154:157], v[210:213], v[26:29]
	v_mfma_f32_16x16x32_bf16 v[26:29], v[158:161], v[214:217], v[26:29]
	v_mfma_f32_16x16x32_bf16 v[10:13], v[154:157], v[230:233], v[10:13]
	v_mfma_f32_16x16x32_bf16 v[10:13], v[158:161], v[234:237], v[10:13]
	s_setprio 0
	s_setprio 1
	v_mfma_f32_16x16x32_bf16 v[54:57], v[162:165], v[178:181], v[54:57]
	v_mfma_f32_16x16x32_bf16 v[54:57], v[166:169], v[182:185], v[54:57]
	v_mfma_f32_16x16x32_bf16 v[38:41], v[162:165], v[186:189], v[38:41]
	v_mfma_f32_16x16x32_bf16 v[38:41], v[166:169], v[190:193], v[38:41]
	v_mfma_f32_16x16x32_bf16 v[22:25], v[162:165], v[210:213], v[22:25]
	v_mfma_f32_16x16x32_bf16 v[22:25], v[166:169], v[214:217], v[22:25]
	v_mfma_f32_16x16x32_bf16 v[6:9], v[162:165], v[230:233], v[6:9]
	v_mfma_f32_16x16x32_bf16 v[6:9], v[166:169], v[234:237], v[6:9]
	v_mfma_f32_16x16x32_bf16 v[50:53], v[170:173], v[178:181], v[50:53]
	v_mfma_f32_16x16x32_bf16 v[50:53], v[174:177], v[182:185], v[50:53]
	v_mfma_f32_16x16x32_bf16 v[34:37], v[170:173], v[186:189], v[34:37]
	v_mfma_f32_16x16x32_bf16 v[34:37], v[174:177], v[190:193], v[34:37]
	v_mfma_f32_16x16x32_bf16 v[18:21], v[170:173], v[210:213], v[18:21]
	v_mfma_f32_16x16x32_bf16 v[18:21], v[174:177], v[214:217], v[18:21]
	v_mfma_f32_16x16x32_bf16 v[2:5], v[170:173], v[230:233], v[2:5]
	v_mfma_f32_16x16x32_bf16 v[2:5], v[174:177], v[234:237], v[2:5]
	s_setprio 0
	s_barrier
	s_add_i32 s28, s28, 2
	s_add_u32 s26, s26, 0x100
	s_addc_u32 s27, s27, 0
	s_add_u32 s90, s90, 0x100
	s_addc_u32 s91, s91, 0
	s_cmp_gt_u32 s28, 29
	s_cbranch_scc0 .LBB0_1609
	s_and_b64 vcc, exec, s[36:37]
	s_cbranch_vccz .LBB0_1612
	s_barrier

.LBB0_1688:
	s_add_u32 s28, s90, 0xffe00080
	s_addc_u32 s29, s91, -1
	s_add_i32 s30, 0, 0x10000
	s_cmpk_eq_i32 s27, 0x7c
	s_cselect_b32 vcc_hi, s21, s29
	s_cselect_b32 vcc_lo, s22, s28
	v_add_u32_e32 v140, s30, v143
	s_cselect_b32 s55, s23, s26
	s_cselect_b32 s54, s24, s25
	s_add_i32 s31, 0, 0x14000
	ds_read_b128 v[146:149], v140
	ds_read_b128 v[150:153], v140 offset:1024
	ds_read_b128 v[154:157], v140 offset:2048
	ds_read_b128 v[158:161], v140 offset:3072
	v_add_u32_e32 v140, s31, v143
	ds_read_b128 v[162:165], v140
	ds_read_b128 v[166:169], v140 offset:1024
	ds_read_b128 v[170:173], v140 offset:2048
	ds_read_b128 v[174:177], v140 offset:3072
	v_lshl_add_u64 v[140:141], s[90:91], 0, v[138:139]
	s_add_i32 m0, s13, 0xc000
	ds_read_b128 v[178:181], v145
	ds_read_b128 v[182:185], v145 offset:1024
	ds_read_b128 v[186:189], v145 offset:2048
	ds_read_b128 v[190:193], v145 offset:3072
	ds_read_b128 v[210:213], v145 offset:4096
	ds_read_b128 v[214:217], v145 offset:5120
	ds_read_b128 v[230:233], v145 offset:6144
	ds_read_b128 v[234:237], v145 offset:7168
	global_load_lds_dwordx4 v[140:141], off
	v_lshl_add_u64 v[140:141], s[90:91], 0, v[136:137]
	s_add_i32 m0, s13, 0xe000
	s_nop 0
	global_load_lds_dwordx4 v[140:141], off
	s_waitcnt vmcnt(8)
	s_waitcnt lgkmcnt(0)
	s_barrier
	s_setprio 1
	s_waitcnt lgkmcnt(0)
	v_mfma_f32_16x16x32_bf16 v[126:129], v[146:149], v[178:181], v[126:129]
	v_mfma_f32_16x16x32_bf16 v[126:129], v[150:153], v[182:185], v[126:129]
	v_mfma_f32_16x16x32_bf16 v[118:121], v[146:149], v[186:189], v[118:121]
	v_mfma_f32_16x16x32_bf16 v[118:121], v[150:153], v[190:193], v[118:121]
	v_mfma_f32_16x16x32_bf16 v[102:105], v[146:149], v[210:213], v[102:105]
	v_mfma_f32_16x16x32_bf16 v[102:105], v[150:153], v[214:217], v[102:105]
	v_mfma_f32_16x16x32_bf16 v[86:89], v[146:149], v[230:233], v[86:89]
	v_mfma_f32_16x16x32_bf16 v[86:89], v[150:153], v[234:237], v[86:89]
	v_mfma_f32_16x16x32_bf16 v[122:125], v[154:157], v[178:181], v[122:125]
	v_mfma_f32_16x16x32_bf16 v[122:125], v[158:161], v[182:185], v[122:125]
	v_mfma_f32_16x16x32_bf16 v[110:113], v[154:157], v[186:189], v[110:113]
	v_mfma_f32_16x16x32_bf16 v[110:113], v[158:161], v[190:193], v[110:113]
	v_mfma_f32_16x16x32_bf16 v[94:97], v[154:157], v[210:213], v[94:97]
	v_mfma_f32_16x16x32_bf16 v[94:97], v[158:161], v[214:217], v[94:97]
	v_mfma_f32_16x16x32_bf16 v[78:81], v[154:157], v[230:233], v[78:81]
	v_mfma_f32_16x16x32_bf16 v[78:81], v[158:161], v[234:237], v[78:81]
	s_setprio 0
	s_setprio 1
	v_mfma_f32_16x16x32_bf16 v[114:117], v[162:165], v[178:181], v[114:117]
	v_mfma_f32_16x16x32_bf16 v[114:117], v[166:169], v[182:185], v[114:117]
	v_mfma_f32_16x16x32_bf16 v[98:101], v[162:165], v[186:189], v[98:101]
	v_mfma_f32_16x16x32_bf16 v[98:101], v[166:169], v[190:193], v[98:101]
	v_mfma_f32_16x16x32_bf16 v[82:85], v[162:165], v[210:213], v[82:85]
	v_mfma_f32_16x16x32_bf16 v[82:85], v[166:169], v[214:217], v[82:85]
	v_mfma_f32_16x16x32_bf16 v[70:73], v[162:165], v[230:233], v[70:73]
	v_mfma_f32_16x16x32_bf16 v[70:73], v[166:169], v[234:237], v[70:73]
	v_mfma_f32_16x16x32_bf16 v[106:109], v[170:173], v[178:181], v[106:109]
	v_mfma_f32_16x16x32_bf16 v[106:109], v[174:177], v[182:185], v[106:109]
	v_mfma_f32_16x16x32_bf16 v[90:93], v[170:173], v[186:189], v[90:93]
	v_mfma_f32_16x16x32_bf16 v[90:93], v[174:177], v[190:193], v[90:93]
	v_mfma_f32_16x16x32_bf16 v[74:77], v[170:173], v[210:213], v[74:77]
	v_mfma_f32_16x16x32_bf16 v[74:77], v[174:177], v[214:217], v[74:77]
	v_mfma_f32_16x16x32_bf16 v[66:69], v[170:173], v[230:233], v[66:69]
	v_mfma_f32_16x16x32_bf16 v[66:69], v[174:177], v[234:237], v[66:69]
	s_setprio 0
	s_barrier
	s_add_i32 s28, s30, s12
	v_lshl_add_u64 v[140:141], s[54:55], 0, v[194:195]
	s_mov_b32 m0, s28
	ds_read_b128 v[178:181], v145 offset:16384
	ds_read_b128 v[182:185], v145 offset:17408
	ds_read_b128 v[186:189], v145 offset:18432
	ds_read_b128 v[190:193], v145 offset:19456
	ds_read_b128 v[210:213], v145 offset:20480
	ds_read_b128 v[214:217], v145 offset:21504
	ds_read_b128 v[230:233], v145 offset:22528
	ds_read_b128 v[234:237], v145 offset:23552
	global_load_lds_dwordx4 v[140:141], off
	s_add_i32 m0, s28, 0x2000
	s_add_u32 s28, s54, 0x200000
	v_lshl_add_u64 v[218:219], s[54:55], 0, v[134:135]
	s_addc_u32 s29, s55, 0
	s_add_i32 s30, s31, s12
	global_load_lds_dwordx4 v[218:219], off
	v_lshl_add_u64 v[238:239], s[28:29], 0, v[194:195]
	s_mov_b32 m0, s30
	v_lshl_add_u64 v[240:241], vcc, 0, v[132:133]
	global_load_lds_dwordx4 v[238:239], off
	v_lshl_add_u64 v[238:239], s[28:29], 0, v[134:135]
	s_add_i32 m0, s30, 0x2000
	s_nop 0
	global_load_lds_dwordx4 v[238:239], off
	v_lshl_add_u64 v[238:239], vcc, 0, v[130:131]
	s_mov_b32 m0, s13
	s_nop 0
	global_load_lds_dwordx4 v[238:239], off
	s_mov_b32 m0, s14
	s_nop 0
	global_load_lds_dwordx4 v[240:241], off
	s_waitcnt vmcnt(8)
	s_waitcnt lgkmcnt(0)
	s_barrier
	s_setprio 1
	s_waitcnt lgkmcnt(0)
	v_mfma_f32_16x16x32_bf16 v[62:65], v[146:149], v[178:181], v[62:65]
	v_mfma_f32_16x16x32_bf16 v[62:65], v[150:153], v[182:185], v[62:65]
	v_mfma_f32_16x16x32_bf16 v[54:57], v[146:149], v[186:189], v[54:57]
	v_mfma_f32_16x16x32_bf16 v[54:57], v[150:153], v[190:193], v[54:57]
	v_mfma_f32_16x16x32_bf16 v[38:41], v[146:149], v[210:213], v[38:41]
	v_mfma_f32_16x16x32_bf16 v[38:41], v[150:153], v[214:217], v[38:41]
	v_mfma_f32_16x16x32_bf16 v[22:25], v[146:149], v[230:233], v[22:25]
	v_mfma_f32_16x16x32_bf16 v[22:25], v[150:153], v[234:237], v[22:25]
	v_mfma_f32_16x16x32_bf16 v[58:61], v[154:157], v[178:181], v[58:61]
	v_mfma_f32_16x16x32_bf16 v[58:61], v[158:161], v[182:185], v[58:61]
	v_mfma_f32_16x16x32_bf16 v[46:49], v[154:157], v[186:189], v[46:49]
	v_mfma_f32_16x16x32_bf16 v[46:49], v[158:161], v[190:193], v[46:49]
	v_mfma_f32_16x16x32_bf16 v[30:33], v[154:157], v[210:213], v[30:33]
	v_mfma_f32_16x16x32_bf16 v[30:33], v[158:161], v[214:217], v[30:33]
	v_mfma_f32_16x16x32_bf16 v[14:17], v[154:157], v[230:233], v[14:17]
	v_mfma_f32_16x16x32_bf16 v[14:17], v[158:161], v[234:237], v[14:17]
	s_setprio 0
	s_setprio 1
	v_mfma_f32_16x16x32_bf16 v[50:53], v[162:165], v[178:181], v[50:53]
	v_mfma_f32_16x16x32_bf16 v[50:53], v[166:169], v[182:185], v[50:53]
	v_mfma_f32_16x16x32_bf16 v[34:37], v[162:165], v[186:189], v[34:37]
	v_mfma_f32_16x16x32_bf16 v[34:37], v[166:169], v[190:193], v[34:37]
	v_mfma_f32_16x16x32_bf16 v[18:21], v[162:165], v[210:213], v[18:21]
	v_mfma_f32_16x16x32_bf16 v[18:21], v[166:169], v[214:217], v[18:21]
	v_mfma_f32_16x16x32_bf16 v[6:9], v[162:165], v[230:233], v[6:9]
	v_mfma_f32_16x16x32_bf16 v[6:9], v[166:169], v[234:237], v[6:9]
	v_mfma_f32_16x16x32_bf16 v[42:45], v[170:173], v[178:181], v[42:45]
	v_mfma_f32_16x16x32_bf16 v[42:45], v[174:177], v[182:185], v[42:45]
	v_mfma_f32_16x16x32_bf16 v[26:29], v[170:173], v[186:189], v[26:29]
	v_mfma_f32_16x16x32_bf16 v[26:29], v[174:177], v[190:193], v[26:29]
	v_mfma_f32_16x16x32_bf16 v[10:13], v[170:173], v[210:213], v[10:13]
	v_mfma_f32_16x16x32_bf16 v[10:13], v[174:177], v[214:217], v[10:13]
	v_mfma_f32_16x16x32_bf16 v[2:5], v[170:173], v[230:233], v[2:5]
	v_mfma_f32_16x16x32_bf16 v[2:5], v[174:177], v[234:237], v[2:5]
	s_setprio 0
	s_barrier
	s_add_i32 s30, 0, 0x18000
	s_add_i32 s31, 0, 0x1c000
	v_add_u32_e32 v158, s30, v143
	v_add_u32_e32 v174, s31, v143
	ds_read_b128 v[146:149], v158
	ds_read_b128 v[150:153], v158 offset:1024
	ds_read_b128 v[154:157], v158 offset:2048
	ds_read_b128 v[158:161], v158 offset:3072
	ds_read_b128 v[162:165], v174
	ds_read_b128 v[166:169], v174 offset:1024
	ds_read_b128 v[170:173], v174 offset:2048
	ds_read_b128 v[174:177], v174 offset:3072
	s_add_u32 s28, vcc_lo, 0x200000
	s_addc_u32 s29, vcc_hi, 0
	s_mov_b32 m0, s15
	v_lshl_add_u64 v[242:243], s[28:29], 0, v[130:131]
	ds_read_b128 v[178:181], v145 offset:32768
	ds_read_b128 v[182:185], v145 offset:33792
	ds_read_b128 v[186:189], v145 offset:34816
	ds_read_b128 v[190:193], v145 offset:35840
	ds_read_b128 v[210:213], v145 offset:36864
	ds_read_b128 v[214:217], v145 offset:37888
	ds_read_b128 v[230:233], v145 offset:38912
	ds_read_b128 v[234:237], v145 offset:39936
	global_load_lds_dwordx4 v[242:243], off
	v_lshl_add_u64 v[242:243], s[28:29], 0, v[132:133]
	s_mov_b32 m0, s16
	s_nop 0
	global_load_lds_dwordx4 v[242:243], off
	s_waitcnt vmcnt(8)
	s_waitcnt lgkmcnt(0)
	s_barrier
	s_setprio 1
	s_waitcnt lgkmcnt(0)
	v_mfma_f32_16x16x32_bf16 v[126:129], v[146:149], v[178:181], v[126:129]
	v_mfma_f32_16x16x32_bf16 v[126:129], v[150:153], v[182:185], v[126:129]
	v_mfma_f32_16x16x32_bf16 v[118:121], v[146:149], v[186:189], v[118:121]
	v_mfma_f32_16x16x32_bf16 v[118:121], v[150:153], v[190:193], v[118:121]
	v_mfma_f32_16x16x32_bf16 v[102:105], v[146:149], v[210:213], v[102:105]
	v_mfma_f32_16x16x32_bf16 v[102:105], v[150:153], v[214:217], v[102:105]
	v_mfma_f32_16x16x32_bf16 v[86:89], v[146:149], v[230:233], v[86:89]
	v_mfma_f32_16x16x32_bf16 v[86:89], v[150:153], v[234:237], v[86:89]
	v_mfma_f32_16x16x32_bf16 v[122:125], v[154:157], v[178:181], v[122:125]
	v_mfma_f32_16x16x32_bf16 v[122:125], v[158:161], v[182:185], v[122:125]
	v_mfma_f32_16x16x32_bf16 v[110:113], v[154:157], v[186:189], v[110:113]
	v_mfma_f32_16x16x32_bf16 v[110:113], v[158:161], v[190:193], v[110:113]
	v_mfma_f32_16x16x32_bf16 v[94:97], v[154:157], v[210:213], v[94:97]
	v_mfma_f32_16x16x32_bf16 v[94:97], v[158:161], v[214:217], v[94:97]
	v_mfma_f32_16x16x32_bf16 v[78:81], v[154:157], v[230:233], v[78:81]
	v_mfma_f32_16x16x32_bf16 v[78:81], v[158:161], v[234:237], v[78:81]
	s_setprio 0
	s_setprio 1
	v_mfma_f32_16x16x32_bf16 v[114:117], v[162:165], v[178:181], v[114:117]
	v_mfma_f32_16x16x32_bf16 v[114:117], v[166:169], v[182:185], v[114:117]
	v_mfma_f32_16x16x32_bf16 v[98:101], v[162:165], v[186:189], v[98:101]
	v_mfma_f32_16x16x32_bf16 v[98:101], v[166:169], v[190:193], v[98:101]
	v_mfma_f32_16x16x32_bf16 v[82:85], v[162:165], v[210:213], v[82:85]
	v_mfma_f32_16x16x32_bf16 v[82:85], v[166:169], v[214:217], v[82:85]
	v_mfma_f32_16x16x32_bf16 v[70:73], v[162:165], v[230:233], v[70:73]
	v_mfma_f32_16x16x32_bf16 v[70:73], v[166:169], v[234:237], v[70:73]
	v_mfma_f32_16x16x32_bf16 v[106:109], v[170:173], v[178:181], v[106:109]
	v_mfma_f32_16x16x32_bf16 v[106:109], v[174:177], v[182:185], v[106:109]
	v_mfma_f32_16x16x32_bf16 v[90:93], v[170:173], v[186:189], v[90:93]
	v_mfma_f32_16x16x32_bf16 v[90:93], v[174:177], v[190:193], v[90:93]
	v_mfma_f32_16x16x32_bf16 v[74:77], v[170:173], v[210:213], v[74:77]
	v_mfma_f32_16x16x32_bf16 v[74:77], v[174:177], v[214:217], v[74:77]
	v_mfma_f32_16x16x32_bf16 v[66:69], v[170:173], v[230:233], v[66:69]
	v_mfma_f32_16x16x32_bf16 v[66:69], v[174:177], v[234:237], v[66:69]
	s_setprio 0
	s_barrier
	s_add_i32 s28, s30, s12
	v_lshl_add_u64 v[140:141], v[140:141], 0, s[56:57]
	s_mov_b32 m0, s28
	ds_read_b128 v[178:181], v145 offset:49152
	ds_read_b128 v[182:185], v145 offset:50176
	ds_read_b128 v[186:189], v145 offset:51200
	ds_read_b128 v[190:193], v145 offset:52224
	ds_read_b128 v[210:213], v145 offset:53248
	ds_read_b128 v[214:217], v145 offset:54272
	ds_read_b128 v[230:233], v145 offset:55296
	ds_read_b128 v[234:237], v145 offset:56320
	global_load_lds_dwordx4 v[140:141], off
	s_add_i32 m0, s28, 0x2000
	s_add_u32 s28, s54, 0x200080
	v_lshl_add_u64 v[140:141], v[218:219], 0, s[56:57]
	s_addc_u32 s29, s55, 0
	s_add_i32 s30, s31, s12
	global_load_lds_dwordx4 v[140:141], off
	v_lshl_add_u64 v[140:141], s[28:29], 0, v[194:195]
	s_mov_b32 m0, s30
	s_nop 0
	global_load_lds_dwordx4 v[140:141], off
	v_lshl_add_u64 v[140:141], s[28:29], 0, v[134:135]
	s_add_i32 m0, s30, 0x2000
	s_nop 0
	global_load_lds_dwordx4 v[140:141], off
	v_lshl_add_u64 v[140:141], v[238:239], 0, s[56:57]
	s_mov_b32 m0, s17
	s_nop 0
	global_load_lds_dwordx4 v[140:141], off
	v_lshl_add_u64 v[140:141], v[240:241], 0, s[56:57]
	s_mov_b32 m0, s18
	s_nop 0
	global_load_lds_dwordx4 v[140:141], off
	s_waitcnt vmcnt(8)
	s_waitcnt lgkmcnt(0)
	s_barrier
	s_setprio 1
	s_waitcnt lgkmcnt(0)
	v_mfma_f32_16x16x32_bf16 v[62:65], v[146:149], v[178:181], v[62:65]
	v_mfma_f32_16x16x32_bf16 v[62:65], v[150:153], v[182:185], v[62:65]
	v_mfma_f32_16x16x32_bf16 v[54:57], v[146:149], v[186:189], v[54:57]
	v_mfma_f32_16x16x32_bf16 v[54:57], v[150:153], v[190:193], v[54:57]
	v_mfma_f32_16x16x32_bf16 v[38:41], v[146:149], v[210:213], v[38:41]
	v_mfma_f32_16x16x32_bf16 v[38:41], v[150:153], v[214:217], v[38:41]
	v_mfma_f32_16x16x32_bf16 v[22:25], v[146:149], v[230:233], v[22:25]
	v_mfma_f32_16x16x32_bf16 v[22:25], v[150:153], v[234:237], v[22:25]
	v_mfma_f32_16x16x32_bf16 v[58:61], v[154:157], v[178:181], v[58:61]
	v_mfma_f32_16x16x32_bf16 v[58:61], v[158:161], v[182:185], v[58:61]
	v_mfma_f32_16x16x32_bf16 v[46:49], v[154:157], v[186:189], v[46:49]
	v_mfma_f32_16x16x32_bf16 v[46:49], v[158:161], v[190:193], v[46:49]
	v_mfma_f32_16x16x32_bf16 v[30:33], v[154:157], v[210:213], v[30:33]
	v_mfma_f32_16x16x32_bf16 v[30:33], v[158:161], v[214:217], v[30:33]
	v_mfma_f32_16x16x32_bf16 v[14:17], v[154:157], v[230:233], v[14:17]
	v_mfma_f32_16x16x32_bf16 v[14:17], v[158:161], v[234:237], v[14:17]
	s_setprio 0
	s_setprio 1
	v_mfma_f32_16x16x32_bf16 v[50:53], v[162:165], v[178:181], v[50:53]
	v_mfma_f32_16x16x32_bf16 v[50:53], v[166:169], v[182:185], v[50:53]
	v_mfma_f32_16x16x32_bf16 v[34:37], v[162:165], v[186:189], v[34:37]
	v_mfma_f32_16x16x32_bf16 v[34:37], v[166:169], v[190:193], v[34:37]
	v_mfma_f32_16x16x32_bf16 v[18:21], v[162:165], v[210:213], v[18:21]
	v_mfma_f32_16x16x32_bf16 v[18:21], v[166:169], v[214:217], v[18:21]
	v_mfma_f32_16x16x32_bf16 v[6:9], v[162:165], v[230:233], v[6:9]
	v_mfma_f32_16x16x32_bf16 v[6:9], v[166:169], v[234:237], v[6:9]
	v_mfma_f32_16x16x32_bf16 v[42:45], v[170:173], v[178:181], v[42:45]
	v_mfma_f32_16x16x32_bf16 v[42:45], v[174:177], v[182:185], v[42:45]
	v_mfma_f32_16x16x32_bf16 v[26:29], v[170:173], v[186:189], v[26:29]
	v_mfma_f32_16x16x32_bf16 v[26:29], v[174:177], v[190:193], v[26:29]
	v_mfma_f32_16x16x32_bf16 v[10:13], v[170:173], v[210:213], v[10:13]
	v_mfma_f32_16x16x32_bf16 v[10:13], v[174:177], v[214:217], v[10:13]
	v_mfma_f32_16x16x32_bf16 v[2:5], v[170:173], v[230:233], v[2:5]
	v_mfma_f32_16x16x32_bf16 v[2:5], v[174:177], v[234:237], v[2:5]
	s_setprio 0
	s_barrier
	s_add_i32 s27, s27, 2
	s_add_u32 s25, s25, 0x100
	s_addc_u32 s26, s26, 0
	s_add_u32 s90, s90, 0x100
	s_addc_u32 s91, s91, 0
	s_cmpk_gt_u32 s27, 0x7d
	s_cbranch_scc0 .LBB0_1688
	s_and_b64 vcc, exec, s[52:53]
	s_cbranch_vccz .LBB0_1691
	s_barrier
